# streaming hint removed from loads that touch a cache line in several instructions: bf16 residual rows, gate z rows, Q rows
# speedup vs baseline: 1.0147x; 1.0147x over previous
.LBB0_70:
	s_add_i32 s14, s94, -7
	s_cmp_lt_u32 s14, -11
	v_mov_b32_e32 v0, s2
	s_movk_i32 s18, 0xffc0
	s_cselect_b64 s[14:15], -1, 0
	v_bfi_b32 v150, s18, v0, v160
	s_lshl_b32 s18, s55, 3
	s_add_i32 s18, s18, s0
	s_ashr_i32 s19, s18, 31
	s_lshl_b64 s[18:19], s[18:19], 17
	s_add_u32 s18, s10, s18
	s_addc_u32 s19, s11, s19
	s_add_u32 s42, s18, 0x1ce00000
	s_addc_u32 s43, s19, 0
	v_readlane_b32 s18, v238, 6
	v_readlane_b32 s19, v238, 7
	s_or_b64 s[18:19], s[14:15], s[18:19]
	s_xor_b64 s[36:37], s[18:19], -1
	v_mov_b32_e32 v136, 0
	s_and_b64 vcc, exec, s[36:37]
	v_ashrrev_i32_e32 v151, 31, v150
	v_mov_b32_e32 v137, 0
	v_mov_b32_e32 v138, 0
	v_mov_b32_e32 v139, 0
	s_mov_b64 s[84:85], s[72:73]
	s_mov_b32 s87, s75
	s_barrier
	s_lshl_b32 s14, s29, 5
	s_lshl_b32 s15, s0, 8
	s_or_b32 s14, s15, s14
	v_lshrrev_b32_e32 v0, 2, v160
	s_lshl_b32 s44, s55, 8
	v_and_or_b32 v152, v0, 12, s14
	s_add_i32 s14, s44, s81
	v_or_b32_e32 v154, s14, v161
	v_ashrrev_i32_e32 v153, 31, v152
	s_cbranch_vccnz .Lres_f32
	v_lshlrev_b32_e32 v158, 4, v150
	v_lshlrev_b32_e32 v159, 1, v152
	v_lshl_add_u32 v0, v154, 12, v159
	v_add_u32_e32 v159, 0x2000, v158
	v_readlane_b32 s6, v236, 43
	v_readlane_b32 s7, v236, 44
	s_mov_b64 s[36:37], s[42:43]
	s_mov_b64 s[38:39], s[6:7]
	global_load_dwordx4 v[142:145], v158, s[36:37] nt
	global_load_dwordx4 v[146:149], v159, s[36:37] nt
	global_load_dwordx2 v[134:135], v0, s[38:39]
	global_load_dwordx2 v[136:137], v0, s[38:39] offset:32
	global_load_dwordx2 v[154:155], v0, s[38:39] offset:256
	global_load_dwordx2 v[156:157], v0, s[38:39] offset:288
	s_add_u32 s36, s42, 0x4000
	s_addc_u32 s37, s43, 0
	s_add_u32 s38, s6, 0x10000
	s_addc_u32 s39, s7, 0
	global_load_dwordx4 v[170:173], v158, s[36:37] nt
	global_load_dwordx4 v[174:177], v159, s[36:37] nt
	global_load_dwordx2 v[178:179], v0, s[38:39]
	global_load_dwordx2 v[180:181], v0, s[38:39] offset:32
	global_load_dwordx2 v[182:183], v0, s[38:39] offset:256
	global_load_dwordx2 v[184:185], v0, s[38:39] offset:288
	s_add_u32 s36, s42, 0x8000
	s_addc_u32 s37, s43, 0
	s_add_u32 s38, s6, 0x20000
	s_addc_u32 s39, s7, 0
	global_load_dwordx4 v[216:219], v158, s[36:37] nt
	global_load_dwordx4 v[220:223], v159, s[36:37] nt
	global_load_dwordx2 v[224:225], v0, s[38:39]
	global_load_dwordx2 v[226:227], v0, s[38:39] offset:32
	global_load_dwordx2 v[228:229], v0, s[38:39] offset:256
	global_load_dwordx2 v[230:231], v0, s[38:39] offset:288
	s_add_u32 s36, s42, 0xc000
	s_addc_u32 s37, s43, 0
	s_add_u32 s38, s6, 0x30000
	s_addc_u32 s39, s7, 0
	global_load_dwordx4 v[190:193], v158, s[36:37] nt
	global_load_dwordx4 v[194:197], v159, s[36:37] nt
	global_load_dwordx2 v[198:199], v0, s[38:39]
	global_load_dwordx2 v[200:201], v0, s[38:39] offset:32
	global_load_dwordx2 v[162:163], v0, s[38:39] offset:256
	global_load_dwordx2 v[164:165], v0, s[38:39] offset:288
	s_waitcnt vmcnt(18)
	v_lshlrev_b32_e32 v130, 16, v142
	v_and_b32_e32 v131, 0xffff0000, v142
	v_lshlrev_b32_e32 v132, 16, v143
	v_and_b32_e32 v133, 0xffff0000, v143
	v_lshlrev_b32_e32 v138, 16, v134
	v_and_b32_e32 v139, 0xffff0000, v134
	v_lshlrev_b32_e32 v140, 16, v135
	v_and_b32_e32 v141, 0xffff0000, v135
	v_pk_add_f32 v[130:131], v[130:131], v[138:139]
	v_pk_add_f32 v[132:133], v[132:133], v[140:141]
	v_pk_fma_f32 v[90:91], v[130:131], s[86:87], v[90:91] op_sel_hi:[1,0,1]
	v_pk_fma_f32 v[92:93], v[132:133], s[86:87], v[92:93] op_sel_hi:[1,0,1]
	v_lshlrev_b32_e32 v130, 16, v144
	v_and_b32_e32 v131, 0xffff0000, v144
	v_lshlrev_b32_e32 v132, 16, v145
	v_and_b32_e32 v133, 0xffff0000, v145
	v_lshlrev_b32_e32 v138, 16, v136
	v_and_b32_e32 v139, 0xffff0000, v136
	v_lshlrev_b32_e32 v140, 16, v137
	v_and_b32_e32 v141, 0xffff0000, v137
	v_pk_add_f32 v[130:131], v[130:131], v[138:139]
	v_pk_add_f32 v[132:133], v[132:133], v[140:141]
	v_pk_fma_f32 v[74:75], v[130:131], s[86:87], v[74:75] op_sel_hi:[1,0,1]
	v_pk_fma_f32 v[76:77], v[132:133], s[86:87], v[76:77] op_sel_hi:[1,0,1]
	v_lshlrev_b32_e32 v130, 16, v146
	v_and_b32_e32 v131, 0xffff0000, v146
	v_lshlrev_b32_e32 v132, 16, v147
	v_and_b32_e32 v133, 0xffff0000, v147
	v_lshlrev_b32_e32 v138, 16, v154
	v_and_b32_e32 v139, 0xffff0000, v154
	v_lshlrev_b32_e32 v140, 16, v155
	v_and_b32_e32 v141, 0xffff0000, v155
	v_pk_add_f32 v[130:131], v[130:131], v[138:139]
	v_pk_add_f32 v[132:133], v[132:133], v[140:141]
	v_pk_fma_f32 v[6:7], v[130:131], s[86:87], v[6:7] op_sel_hi:[1,0,1]
	v_pk_fma_f32 v[8:9], v[132:133], s[86:87], v[8:9] op_sel_hi:[1,0,1]
	v_lshlrev_b32_e32 v130, 16, v148
	v_and_b32_e32 v131, 0xffff0000, v148
	v_lshlrev_b32_e32 v132, 16, v149
	v_and_b32_e32 v133, 0xffff0000, v149
	v_lshlrev_b32_e32 v138, 16, v156
	v_and_b32_e32 v139, 0xffff0000, v156
	v_lshlrev_b32_e32 v140, 16, v157
	v_and_b32_e32 v141, 0xffff0000, v157
	v_pk_add_f32 v[130:131], v[130:131], v[138:139]
	v_pk_add_f32 v[132:133], v[132:133], v[140:141]
	v_pk_fma_f32 v[2:3], v[130:131], s[86:87], v[2:3] op_sel_hi:[1,0,1]
	v_pk_fma_f32 v[4:5], v[132:133], s[86:87], v[4:5] op_sel_hi:[1,0,1]
	s_add_u32 s36, s42, 0x10000
	s_addc_u32 s37, s43, 0
	s_add_u32 s38, s6, 0x80000
	s_addc_u32 s39, s7, 0
	global_load_dwordx4 v[142:145], v158, s[36:37] nt
	global_load_dwordx4 v[146:149], v159, s[36:37] nt
	global_load_dwordx2 v[134:135], v0, s[38:39]
	global_load_dwordx2 v[136:137], v0, s[38:39] offset:32
	global_load_dwordx2 v[154:155], v0, s[38:39] offset:256
	global_load_dwordx2 v[156:157], v0, s[38:39] offset:288
	s_waitcnt vmcnt(18)
	v_lshlrev_b32_e32 v130, 16, v170
	v_and_b32_e32 v131, 0xffff0000, v170
	v_lshlrev_b32_e32 v132, 16, v171
	v_and_b32_e32 v133, 0xffff0000, v171
	v_lshlrev_b32_e32 v138, 16, v178
	v_and_b32_e32 v139, 0xffff0000, v178
	v_lshlrev_b32_e32 v140, 16, v179
	v_and_b32_e32 v141, 0xffff0000, v179
	v_pk_add_f32 v[130:131], v[130:131], v[138:139]
	v_pk_add_f32 v[132:133], v[132:133], v[140:141]
	v_pk_fma_f32 v[94:95], v[130:131], s[86:87], v[94:95] op_sel_hi:[1,0,1]
	v_pk_fma_f32 v[96:97], v[132:133], s[86:87], v[96:97] op_sel_hi:[1,0,1]
	v_lshlrev_b32_e32 v130, 16, v172
	v_and_b32_e32 v131, 0xffff0000, v172
	v_lshlrev_b32_e32 v132, 16, v173
	v_and_b32_e32 v133, 0xffff0000, v173
	v_lshlrev_b32_e32 v138, 16, v180
	v_and_b32_e32 v139, 0xffff0000, v180
	v_lshlrev_b32_e32 v140, 16, v181
	v_and_b32_e32 v141, 0xffff0000, v181
	v_pk_add_f32 v[130:131], v[130:131], v[138:139]
	v_pk_add_f32 v[132:133], v[132:133], v[140:141]
	v_pk_fma_f32 v[78:79], v[130:131], s[86:87], v[78:79] op_sel_hi:[1,0,1]
	v_pk_fma_f32 v[80:81], v[132:133], s[86:87], v[80:81] op_sel_hi:[1,0,1]
	v_lshlrev_b32_e32 v130, 16, v174
	v_and_b32_e32 v131, 0xffff0000, v174
	v_lshlrev_b32_e32 v132, 16, v175
	v_and_b32_e32 v133, 0xffff0000, v175
	v_lshlrev_b32_e32 v138, 16, v182
	v_and_b32_e32 v139, 0xffff0000, v182
	v_lshlrev_b32_e32 v140, 16, v183
	v_and_b32_e32 v141, 0xffff0000, v183
	v_pk_add_f32 v[130:131], v[130:131], v[138:139]
	v_pk_add_f32 v[132:133], v[132:133], v[140:141]
	v_pk_fma_f32 v[14:15], v[130:131], s[86:87], v[14:15] op_sel_hi:[1,0,1]
	v_pk_fma_f32 v[16:17], v[132:133], s[86:87], v[16:17] op_sel_hi:[1,0,1]
	v_lshlrev_b32_e32 v130, 16, v176
	v_and_b32_e32 v131, 0xffff0000, v176
	v_lshlrev_b32_e32 v132, 16, v177
	v_and_b32_e32 v133, 0xffff0000, v177
	v_lshlrev_b32_e32 v138, 16, v184
	v_and_b32_e32 v139, 0xffff0000, v184
	v_lshlrev_b32_e32 v140, 16, v185
	v_and_b32_e32 v141, 0xffff0000, v185
	v_pk_add_f32 v[130:131], v[130:131], v[138:139]
	v_pk_add_f32 v[132:133], v[132:133], v[140:141]
	v_pk_fma_f32 v[10:11], v[130:131], s[86:87], v[10:11] op_sel_hi:[1,0,1]
	v_pk_fma_f32 v[12:13], v[132:133], s[86:87], v[12:13] op_sel_hi:[1,0,1]
	s_add_u32 s36, s42, 0x14000
	s_addc_u32 s37, s43, 0
	s_add_u32 s38, s6, 0x90000
	s_addc_u32 s39, s7, 0
	global_load_dwordx4 v[170:173], v158, s[36:37] nt
	global_load_dwordx4 v[174:177], v159, s[36:37] nt
	global_load_dwordx2 v[178:179], v0, s[38:39]
	global_load_dwordx2 v[180:181], v0, s[38:39] offset:32
	global_load_dwordx2 v[182:183], v0, s[38:39] offset:256
	global_load_dwordx2 v[184:185], v0, s[38:39] offset:288
	s_waitcnt vmcnt(18)
	v_lshlrev_b32_e32 v130, 16, v216
	v_and_b32_e32 v131, 0xffff0000, v216
	v_lshlrev_b32_e32 v132, 16, v217
	v_and_b32_e32 v133, 0xffff0000, v217
	v_lshlrev_b32_e32 v138, 16, v224
	v_and_b32_e32 v139, 0xffff0000, v224
	v_lshlrev_b32_e32 v140, 16, v225
	v_and_b32_e32 v141, 0xffff0000, v225
	v_pk_add_f32 v[130:131], v[130:131], v[138:139]
	v_pk_add_f32 v[132:133], v[132:133], v[140:141]
	v_pk_fma_f32 v[102:103], v[130:131], s[86:87], v[102:103] op_sel_hi:[1,0,1]
	v_pk_fma_f32 v[104:105], v[132:133], s[86:87], v[104:105] op_sel_hi:[1,0,1]
	v_lshlrev_b32_e32 v130, 16, v218
	v_and_b32_e32 v131, 0xffff0000, v218
	v_lshlrev_b32_e32 v132, 16, v219
	v_and_b32_e32 v133, 0xffff0000, v219
	v_lshlrev_b32_e32 v138, 16, v226
	v_and_b32_e32 v139, 0xffff0000, v226
	v_lshlrev_b32_e32 v140, 16, v227
	v_and_b32_e32 v141, 0xffff0000, v227
	v_pk_add_f32 v[130:131], v[130:131], v[138:139]
	v_pk_add_f32 v[132:133], v[132:133], v[140:141]
	v_pk_fma_f32 v[98:99], v[130:131], s[86:87], v[98:99] op_sel_hi:[1,0,1]
	v_pk_fma_f32 v[100:101], v[132:133], s[86:87], v[100:101] op_sel_hi:[1,0,1]
	v_lshlrev_b32_e32 v130, 16, v220
	v_and_b32_e32 v131, 0xffff0000, v220
	v_lshlrev_b32_e32 v132, 16, v221
	v_and_b32_e32 v133, 0xffff0000, v221
	v_lshlrev_b32_e32 v138, 16, v228
	v_and_b32_e32 v139, 0xffff0000, v228
	v_lshlrev_b32_e32 v140, 16, v229
	v_and_b32_e32 v141, 0xffff0000, v229
	v_pk_add_f32 v[130:131], v[130:131], v[138:139]
	v_pk_add_f32 v[132:133], v[132:133], v[140:141]
	v_pk_fma_f32 v[22:23], v[130:131], s[86:87], v[22:23] op_sel_hi:[1,0,1]
	v_pk_fma_f32 v[24:25], v[132:133], s[86:87], v[24:25] op_sel_hi:[1,0,1]
	v_lshlrev_b32_e32 v130, 16, v222
	v_and_b32_e32 v131, 0xffff0000, v222
	v_lshlrev_b32_e32 v132, 16, v223
	v_and_b32_e32 v133, 0xffff0000, v223
	v_lshlrev_b32_e32 v138, 16, v230
	v_and_b32_e32 v139, 0xffff0000, v230
	v_lshlrev_b32_e32 v140, 16, v231
	v_and_b32_e32 v141, 0xffff0000, v231
	v_pk_add_f32 v[130:131], v[130:131], v[138:139]
	v_pk_add_f32 v[132:133], v[132:133], v[140:141]
	v_pk_fma_f32 v[18:19], v[130:131], s[86:87], v[18:19] op_sel_hi:[1,0,1]
	v_pk_fma_f32 v[20:21], v[132:133], s[86:87], v[20:21] op_sel_hi:[1,0,1]
	s_add_u32 s36, s42, 0x18000
	s_addc_u32 s37, s43, 0
	s_add_u32 s38, s6, 0xa0000
	s_addc_u32 s39, s7, 0
	global_load_dwordx4 v[216:219], v158, s[36:37] nt
	global_load_dwordx4 v[220:223], v159, s[36:37] nt
	global_load_dwordx2 v[224:225], v0, s[38:39]
	global_load_dwordx2 v[226:227], v0, s[38:39] offset:32
	global_load_dwordx2 v[228:229], v0, s[38:39] offset:256
	global_load_dwordx2 v[230:231], v0, s[38:39] offset:288
	s_waitcnt vmcnt(18)
	v_lshlrev_b32_e32 v130, 16, v190
	v_and_b32_e32 v131, 0xffff0000, v190
	v_lshlrev_b32_e32 v132, 16, v191
	v_and_b32_e32 v133, 0xffff0000, v191
	v_lshlrev_b32_e32 v138, 16, v198
	v_and_b32_e32 v139, 0xffff0000, v198
	v_lshlrev_b32_e32 v140, 16, v199
	v_and_b32_e32 v141, 0xffff0000, v199
	v_pk_add_f32 v[130:131], v[130:131], v[138:139]
	v_pk_add_f32 v[132:133], v[132:133], v[140:141]
	v_pk_fma_f32 v[118:119], v[130:131], s[86:87], v[118:119] op_sel_hi:[1,0,1]
	v_pk_fma_f32 v[120:121], v[132:133], s[86:87], v[120:121] op_sel_hi:[1,0,1]
	v_lshlrev_b32_e32 v130, 16, v192
	v_and_b32_e32 v131, 0xffff0000, v192
	v_lshlrev_b32_e32 v132, 16, v193
	v_and_b32_e32 v133, 0xffff0000, v193
	v_lshlrev_b32_e32 v138, 16, v200
	v_and_b32_e32 v139, 0xffff0000, v200
	v_lshlrev_b32_e32 v140, 16, v201
	v_and_b32_e32 v141, 0xffff0000, v201
	v_pk_add_f32 v[130:131], v[130:131], v[138:139]
	v_pk_add_f32 v[132:133], v[132:133], v[140:141]
	v_pk_fma_f32 v[106:107], v[130:131], s[86:87], v[106:107] op_sel_hi:[1,0,1]
	v_pk_fma_f32 v[108:109], v[132:133], s[86:87], v[108:109] op_sel_hi:[1,0,1]
	v_lshlrev_b32_e32 v130, 16, v194
	v_and_b32_e32 v131, 0xffff0000, v194
	v_lshlrev_b32_e32 v132, 16, v195
	v_and_b32_e32 v133, 0xffff0000, v195
	v_lshlrev_b32_e32 v138, 16, v162
	v_and_b32_e32 v139, 0xffff0000, v162
	v_lshlrev_b32_e32 v140, 16, v163
	v_and_b32_e32 v141, 0xffff0000, v163
	v_pk_add_f32 v[130:131], v[130:131], v[138:139]
	v_pk_add_f32 v[132:133], v[132:133], v[140:141]
	v_pk_fma_f32 v[30:31], v[130:131], s[86:87], v[30:31] op_sel_hi:[1,0,1]
	v_pk_fma_f32 v[32:33], v[132:133], s[86:87], v[32:33] op_sel_hi:[1,0,1]
	v_lshlrev_b32_e32 v130, 16, v196
	v_and_b32_e32 v131, 0xffff0000, v196
	v_lshlrev_b32_e32 v132, 16, v197
	v_and_b32_e32 v133, 0xffff0000, v197
	v_lshlrev_b32_e32 v138, 16, v164
	v_and_b32_e32 v139, 0xffff0000, v164
	v_lshlrev_b32_e32 v140, 16, v165
	v_and_b32_e32 v141, 0xffff0000, v165
	v_pk_add_f32 v[130:131], v[130:131], v[138:139]
	v_pk_add_f32 v[132:133], v[132:133], v[140:141]
	v_pk_fma_f32 v[26:27], v[130:131], s[86:87], v[26:27] op_sel_hi:[1,0,1]
	v_pk_fma_f32 v[28:29], v[132:133], s[86:87], v[28:29] op_sel_hi:[1,0,1]
	s_add_u32 s36, s42, 0x1c000
	s_addc_u32 s37, s43, 0
	s_add_u32 s38, s6, 0xb0000
	s_addc_u32 s39, s7, 0
	global_load_dwordx4 v[190:193], v158, s[36:37] nt
	global_load_dwordx4 v[194:197], v159, s[36:37] nt
	global_load_dwordx2 v[198:199], v0, s[38:39]
	global_load_dwordx2 v[200:201], v0, s[38:39] offset:32
	global_load_dwordx2 v[162:163], v0, s[38:39] offset:256
	global_load_dwordx2 v[164:165], v0, s[38:39] offset:288
	s_waitcnt vmcnt(18)
	v_lshlrev_b32_e32 v130, 16, v142
	v_and_b32_e32 v131, 0xffff0000, v142
	v_lshlrev_b32_e32 v132, 16, v143
	v_and_b32_e32 v133, 0xffff0000, v143
	v_lshlrev_b32_e32 v138, 16, v134
	v_and_b32_e32 v139, 0xffff0000, v134
	v_lshlrev_b32_e32 v140, 16, v135
	v_and_b32_e32 v141, 0xffff0000, v135
	v_pk_add_f32 v[130:131], v[130:131], v[138:139]
	v_pk_add_f32 v[132:133], v[132:133], v[140:141]
	v_pk_fma_f32 v[126:127], v[130:131], s[86:87], v[126:127] op_sel_hi:[1,0,1]
	v_pk_fma_f32 v[128:129], v[132:133], s[86:87], v[128:129] op_sel_hi:[1,0,1]
	v_lshlrev_b32_e32 v130, 16, v144
	v_and_b32_e32 v131, 0xffff0000, v144
	v_lshlrev_b32_e32 v132, 16, v145
	v_and_b32_e32 v133, 0xffff0000, v145
	v_lshlrev_b32_e32 v138, 16, v136
	v_and_b32_e32 v139, 0xffff0000, v136
	v_lshlrev_b32_e32 v140, 16, v137
	v_and_b32_e32 v141, 0xffff0000, v137
	v_pk_add_f32 v[130:131], v[130:131], v[138:139]
	v_pk_add_f32 v[132:133], v[132:133], v[140:141]
	v_pk_fma_f32 v[122:123], v[130:131], s[86:87], v[122:123] op_sel_hi:[1,0,1]
	v_pk_fma_f32 v[124:125], v[132:133], s[86:87], v[124:125] op_sel_hi:[1,0,1]
	v_lshlrev_b32_e32 v130, 16, v146
	v_and_b32_e32 v131, 0xffff0000, v146
	v_lshlrev_b32_e32 v132, 16, v147
	v_and_b32_e32 v133, 0xffff0000, v147
	v_lshlrev_b32_e32 v138, 16, v154
	v_and_b32_e32 v139, 0xffff0000, v154
	v_lshlrev_b32_e32 v140, 16, v155
	v_and_b32_e32 v141, 0xffff0000, v155
	v_pk_add_f32 v[130:131], v[130:131], v[138:139]
	v_pk_add_f32 v[132:133], v[132:133], v[140:141]
	v_pk_fma_f32 v[38:39], v[130:131], s[86:87], v[38:39] op_sel_hi:[1,0,1]
	v_pk_fma_f32 v[40:41], v[132:133], s[86:87], v[40:41] op_sel_hi:[1,0,1]
	v_lshlrev_b32_e32 v130, 16, v148
	v_and_b32_e32 v131, 0xffff0000, v148
	v_lshlrev_b32_e32 v132, 16, v149
	v_and_b32_e32 v133, 0xffff0000, v149
	v_lshlrev_b32_e32 v138, 16, v156
	v_and_b32_e32 v139, 0xffff0000, v156
	v_lshlrev_b32_e32 v140, 16, v157
	v_and_b32_e32 v141, 0xffff0000, v157
	v_pk_add_f32 v[130:131], v[130:131], v[138:139]
	v_pk_add_f32 v[132:133], v[132:133], v[140:141]
	v_pk_fma_f32 v[34:35], v[130:131], s[86:87], v[34:35] op_sel_hi:[1,0,1]
	v_pk_fma_f32 v[36:37], v[132:133], s[86:87], v[36:37] op_sel_hi:[1,0,1]
	s_waitcnt vmcnt(12)
	v_lshlrev_b32_e32 v130, 16, v170
	v_and_b32_e32 v131, 0xffff0000, v170
	v_lshlrev_b32_e32 v132, 16, v171
	v_and_b32_e32 v133, 0xffff0000, v171
	v_lshlrev_b32_e32 v138, 16, v178
	v_and_b32_e32 v139, 0xffff0000, v178
	v_lshlrev_b32_e32 v140, 16, v179
	v_and_b32_e32 v141, 0xffff0000, v179
	v_pk_add_f32 v[130:131], v[130:131], v[138:139]
	v_pk_add_f32 v[132:133], v[132:133], v[140:141]
	v_pk_fma_f32 v[114:115], v[130:131], s[86:87], v[114:115] op_sel_hi:[1,0,1]
	v_pk_fma_f32 v[116:117], v[132:133], s[86:87], v[116:117] op_sel_hi:[1,0,1]
	v_lshlrev_b32_e32 v130, 16, v172
	v_and_b32_e32 v131, 0xffff0000, v172
	v_lshlrev_b32_e32 v132, 16, v173
	v_and_b32_e32 v133, 0xffff0000, v173
	v_lshlrev_b32_e32 v138, 16, v180
	v_and_b32_e32 v139, 0xffff0000, v180
	v_lshlrev_b32_e32 v140, 16, v181
	v_and_b32_e32 v141, 0xffff0000, v181
	v_pk_add_f32 v[130:131], v[130:131], v[138:139]
	v_pk_add_f32 v[132:133], v[132:133], v[140:141]
	v_pk_fma_f32 v[110:111], v[130:131], s[86:87], v[110:111] op_sel_hi:[1,0,1]
	v_pk_fma_f32 v[112:113], v[132:133], s[86:87], v[112:113] op_sel_hi:[1,0,1]
	v_lshlrev_b32_e32 v130, 16, v174
	v_and_b32_e32 v131, 0xffff0000, v174
	v_lshlrev_b32_e32 v132, 16, v175
	v_and_b32_e32 v133, 0xffff0000, v175
	v_lshlrev_b32_e32 v138, 16, v182
	v_and_b32_e32 v139, 0xffff0000, v182
	v_lshlrev_b32_e32 v140, 16, v183
	v_and_b32_e32 v141, 0xffff0000, v183
	v_pk_add_f32 v[130:131], v[130:131], v[138:139]
	v_pk_add_f32 v[132:133], v[132:133], v[140:141]
	v_pk_fma_f32 v[46:47], v[130:131], s[86:87], v[46:47] op_sel_hi:[1,0,1]
	v_pk_fma_f32 v[48:49], v[132:133], s[86:87], v[48:49] op_sel_hi:[1,0,1]
	v_lshlrev_b32_e32 v130, 16, v176
	v_and_b32_e32 v131, 0xffff0000, v176
	v_lshlrev_b32_e32 v132, 16, v177
	v_and_b32_e32 v133, 0xffff0000, v177
	v_lshlrev_b32_e32 v138, 16, v184
	v_and_b32_e32 v139, 0xffff0000, v184
	v_lshlrev_b32_e32 v140, 16, v185
	v_and_b32_e32 v141, 0xffff0000, v185
	v_pk_add_f32 v[130:131], v[130:131], v[138:139]
	v_pk_add_f32 v[132:133], v[132:133], v[140:141]
	v_pk_fma_f32 v[42:43], v[130:131], s[86:87], v[42:43] op_sel_hi:[1,0,1]
	v_pk_fma_f32 v[44:45], v[132:133], s[86:87], v[44:45] op_sel_hi:[1,0,1]
	s_waitcnt vmcnt(6)
	v_lshlrev_b32_e32 v130, 16, v216
	v_and_b32_e32 v131, 0xffff0000, v216
	v_lshlrev_b32_e32 v132, 16, v217
	v_and_b32_e32 v133, 0xffff0000, v217
	v_lshlrev_b32_e32 v138, 16, v224
	v_and_b32_e32 v139, 0xffff0000, v224
	v_lshlrev_b32_e32 v140, 16, v225
	v_and_b32_e32 v141, 0xffff0000, v225
	v_pk_add_f32 v[130:131], v[130:131], v[138:139]
	v_pk_add_f32 v[132:133], v[132:133], v[140:141]
	v_pk_fma_f32 v[86:87], v[130:131], s[86:87], v[86:87] op_sel_hi:[1,0,1]
	v_pk_fma_f32 v[88:89], v[132:133], s[86:87], v[88:89] op_sel_hi:[1,0,1]
	v_lshlrev_b32_e32 v130, 16, v218
	v_and_b32_e32 v131, 0xffff0000, v218
	v_lshlrev_b32_e32 v132, 16, v219
	v_and_b32_e32 v133, 0xffff0000, v219
	v_lshlrev_b32_e32 v138, 16, v226
	v_and_b32_e32 v139, 0xffff0000, v226
	v_lshlrev_b32_e32 v140, 16, v227
	v_and_b32_e32 v141, 0xffff0000, v227
	v_pk_add_f32 v[130:131], v[130:131], v[138:139]
	v_pk_add_f32 v[132:133], v[132:133], v[140:141]
	v_pk_fma_f32 v[82:83], v[130:131], s[86:87], v[82:83] op_sel_hi:[1,0,1]
	v_pk_fma_f32 v[84:85], v[132:133], s[86:87], v[84:85] op_sel_hi:[1,0,1]
	v_lshlrev_b32_e32 v130, 16, v220
	v_and_b32_e32 v131, 0xffff0000, v220
	v_lshlrev_b32_e32 v132, 16, v221
	v_and_b32_e32 v133, 0xffff0000, v221
	v_lshlrev_b32_e32 v138, 16, v228
	v_and_b32_e32 v139, 0xffff0000, v228
	v_lshlrev_b32_e32 v140, 16, v229
	v_and_b32_e32 v141, 0xffff0000, v229
	v_pk_add_f32 v[130:131], v[130:131], v[138:139]
	v_pk_add_f32 v[132:133], v[132:133], v[140:141]
	v_pk_fma_f32 v[62:63], v[130:131], s[86:87], v[62:63] op_sel_hi:[1,0,1]
	v_pk_fma_f32 v[64:65], v[132:133], s[86:87], v[64:65] op_sel_hi:[1,0,1]
	v_lshlrev_b32_e32 v130, 16, v222
	v_and_b32_e32 v131, 0xffff0000, v222
	v_lshlrev_b32_e32 v132, 16, v223
	v_and_b32_e32 v133, 0xffff0000, v223
	v_lshlrev_b32_e32 v138, 16, v230
	v_and_b32_e32 v139, 0xffff0000, v230
	v_lshlrev_b32_e32 v140, 16, v231
	v_and_b32_e32 v141, 0xffff0000, v231
	v_pk_add_f32 v[130:131], v[130:131], v[138:139]
	v_pk_add_f32 v[132:133], v[132:133], v[140:141]
	v_pk_fma_f32 v[54:55], v[130:131], s[86:87], v[54:55] op_sel_hi:[1,0,1]
	v_pk_fma_f32 v[56:57], v[132:133], s[86:87], v[56:57] op_sel_hi:[1,0,1]
	s_waitcnt vmcnt(0)
	v_lshlrev_b32_e32 v130, 16, v190
	v_and_b32_e32 v131, 0xffff0000, v190
	v_lshlrev_b32_e32 v132, 16, v191
	v_and_b32_e32 v133, 0xffff0000, v191
	v_lshlrev_b32_e32 v138, 16, v198
	v_and_b32_e32 v139, 0xffff0000, v198
	v_lshlrev_b32_e32 v140, 16, v199
	v_and_b32_e32 v141, 0xffff0000, v199
	v_pk_add_f32 v[130:131], v[130:131], v[138:139]
	v_pk_add_f32 v[132:133], v[132:133], v[140:141]
	v_pk_fma_f32 v[70:71], v[130:131], s[86:87], v[70:71] op_sel_hi:[1,0,1]
	v_pk_fma_f32 v[72:73], v[132:133], s[86:87], v[72:73] op_sel_hi:[1,0,1]
	v_lshlrev_b32_e32 v130, 16, v192
	v_and_b32_e32 v131, 0xffff0000, v192
	v_lshlrev_b32_e32 v132, 16, v193
	v_and_b32_e32 v133, 0xffff0000, v193
	v_lshlrev_b32_e32 v138, 16, v200
	v_and_b32_e32 v139, 0xffff0000, v200
	v_lshlrev_b32_e32 v140, 16, v201
	v_and_b32_e32 v141, 0xffff0000, v201
	v_pk_add_f32 v[130:131], v[130:131], v[138:139]
	v_pk_add_f32 v[132:133], v[132:133], v[140:141]
	v_pk_fma_f32 v[66:67], v[130:131], s[86:87], v[66:67] op_sel_hi:[1,0,1]
	v_pk_fma_f32 v[68:69], v[132:133], s[86:87], v[68:69] op_sel_hi:[1,0,1]
	v_lshlrev_b32_e32 v130, 16, v194
	v_and_b32_e32 v131, 0xffff0000, v194
	v_lshlrev_b32_e32 v132, 16, v195
	v_and_b32_e32 v133, 0xffff0000, v195
	v_lshlrev_b32_e32 v138, 16, v162
	v_and_b32_e32 v139, 0xffff0000, v162
	v_lshlrev_b32_e32 v140, 16, v163
	v_and_b32_e32 v141, 0xffff0000, v163
	v_pk_add_f32 v[130:131], v[130:131], v[138:139]
	v_pk_add_f32 v[132:133], v[132:133], v[140:141]
	v_pk_fma_f32 v[58:59], v[130:131], s[86:87], v[58:59] op_sel_hi:[1,0,1]
	v_pk_fma_f32 v[60:61], v[132:133], s[86:87], v[60:61] op_sel_hi:[1,0,1]
	v_lshlrev_b32_e32 v130, 16, v196
	v_and_b32_e32 v131, 0xffff0000, v196
	v_lshlrev_b32_e32 v132, 16, v197
	v_and_b32_e32 v133, 0xffff0000, v197
	v_lshlrev_b32_e32 v138, 16, v164
	v_and_b32_e32 v139, 0xffff0000, v164
	v_lshlrev_b32_e32 v140, 16, v165
	v_and_b32_e32 v141, 0xffff0000, v165
	v_pk_add_f32 v[130:131], v[130:131], v[138:139]
	v_pk_add_f32 v[132:133], v[132:133], v[140:141]
	v_pk_fma_f32 v[50:51], v[130:131], s[86:87], v[50:51] op_sel_hi:[1,0,1]
	v_pk_fma_f32 v[52:53], v[132:133], s[86:87], v[52:53] op_sel_hi:[1,0,1]
	s_branch .Lres_done

.LBB0_351:
	s_andn2_b64 vcc, exec, s[0:1]
	s_cbranch_vccnz .LBB0_357
	v_readlane_b32 s22, v238, 21
	s_mul_i32 s0, s22, 0x2a00
	s_add_u32 s0, s4, s0
	s_mul_hi_i32 s1, s22, 0x2a00
	s_addc_u32 s1, s5, s1
	v_ashrrev_i32_e32 v128, 3, v104
	v_mov_b64_e32 v[2:3], s[0:1]
	v_readlane_b32 s2, v238, 23
	v_lshlrev_b32_e32 v0, 3, v104
	v_mad_i64_i32 v[2:3], s[14:15], v128, s59, v[2:3]
	s_lshl_b32 s18, s2, 1
	s_mov_b32 s19, s3
	v_and_b32_e32 v0, 56, v0
	v_lshlrev_b32_e32 v18, 1, v0
	v_mov_b32_e32 v19, v1
	v_lshl_add_u64 v[2:3], v[2:3], 0, s[18:19]
	v_lshl_add_u64 v[2:3], v[2:3], 0, v[18:19]
	v_add_co_u32_e32 v2, vcc, s61, v2
	s_add_u32 s36, s10, 0x1c600000
	s_nop 0
	v_addc_co_u32_e32 v3, vcc, 0, v3, vcc
	global_load_dwordx4 v[66:69], v[2:3], off offset:2048 nt
	global_load_dwordx4 v[54:57], v[2:3], off offset:2560 nt
	v_add_u32_e32 v2, s22, v128
	v_ashrrev_i32_e32 v3, 31, v2
	s_addc_u32 s37, s11, 0
	v_lshlrev_b64 v[2:3], 10, v[2:3]
	v_lshl_add_u64 v[2:3], s[36:37], 0, v[2:3]
	s_lshl_b32 s38, s2, 2
	s_mov_b32 s39, s3
	v_lshl_add_u64 v[2:3], v[2:3], 0, s[38:39]
	v_lshlrev_b32_e32 v20, 2, v0
	v_mov_b32_e32 v21, v1
	v_lshl_add_u64 v[2:3], v[2:3], 0, v[20:21]
	global_load_dwordx4 v[74:77], v[2:3], off offset:16 nt
	global_load_dwordx4 v[78:81], v[2:3], off nt
	s_add_u32 s24, s10, 0x1a000000
	s_addc_u32 s25, s11, 0
	v_readlane_b32 s14, v238, 24
	v_readlane_b32 s23, v238, 22
	v_readlane_b32 s15, v238, 25
	s_add_u32 s14, s24, s14
	s_addc_u32 s15, s25, s15
	s_lshl_b64 s[22:23], s[22:23], 1
	s_add_u32 s22, s8, s22
	v_add_u32_e32 v0, 0x200, v104
	s_addc_u32 s23, s9, s23
	v_readlane_b32 s2, v238, 27
	v_ashrrev_i32_e32 v129, 3, v0
	v_lshl_add_u64 v[2:3], s[22:23], 0, v[18:19]
	v_add_u32_e32 v28, s2, v128
	s_movk_i32 s6, 0x4080
	v_add_u32_e32 v29, s2, v129
	v_lshl_add_u64 v[4:5], s[14:15], 0, v[18:19]
	v_mad_i64_i32 v[6:7], s[14:15], v28, s6, v[2:3]
	v_mad_i64_i32 v[2:3], s[14:15], v29, s6, v[2:3]
	global_load_dwordx4 v[50:53], v[6:7], off nt
	global_load_dwordx4 v[62:65], v[2:3], off nt
	v_lshlrev_b32_e32 v6, 6, v128
	v_lshlrev_b32_e32 v2, 6, v129
	v_ashrrev_i32_e32 v7, 31, v6
	v_ashrrev_i32_e32 v3, 31, v2
	v_lshlrev_b64 v[22:23], 1, v[6:7]
	v_lshlrev_b64 v[34:35], 1, v[2:3]
	v_lshl_add_u64 v[6:7], v[4:5], 0, v[22:23]
	v_lshl_add_u64 v[2:3], v[4:5], 0, v[34:35]
	global_load_dwordx4 v[58:61], v[6:7], off nt
	global_load_dwordx4 v[70:73], v[2:3], off nt
	s_lshl_b32 s22, s78, 4
	s_and_b32 s79, s22, 48
	v_or_b32_e32 v105, s79, v102
	v_mul_u32_u24_e32 v2, 0x1500, v105
	v_lshlrev_b32_e32 v84, 1, v2
	v_mov_b32_e32 v85, v1
	v_lshl_add_u64 v[2:3], s[0:1], 0, v[84:85]
	v_readlane_b32 s0, v238, 26
	s_lshl_b32 s2, s0, 1
	v_readlane_b32 s0, v236, 46
	s_lshl_b32 s14, s0, 7
	s_ashr_i32 s15, s14, 31
	v_readlane_b32 s40, v236, 11
	s_and_b32 s0, s22, 0xffffffc0
	s_lshl_b64 s[14:15], s[14:15], 2
	v_readlane_b32 s52, v236, 23
	v_readlane_b32 s1, v236, 47
	v_readlane_b32 s53, v236, 24
	s_add_u32 s14, s52, s14
	v_lshlrev_b32_e32 v0, 2, v103
	s_addc_u32 s15, s53, s15
	s_or_b32 s1, s22, 48
	v_or_b32_e32 v90, s0, v0
	v_or_b32_e32 v82, s1, v0
	v_lshl_add_u64 v[2:3], v[2:3], 0, s[2:3]
	s_mov_b64 s[64:65], 0x1c00
	v_ashrrev_i32_e32 v91, 31, v90
	v_ashrrev_i32_e32 v83, 31, v82
	v_lshl_add_u64 v[2:3], v[2:3], 0, s[64:65]
	v_lshlrev_b64 v[86:87], 1, v[90:91]
	v_readlane_b32 s41, v236, 12
	v_lshlrev_b64 v[106:107], 1, v[82:83]
	v_lshl_add_u64 v[4:5], v[2:3], 0, v[86:87]
	v_lshl_add_u64 v[6:7], v[90:91], 2, s[14:15]
	v_lshl_add_u64 v[2:3], v[2:3], 0, v[106:107]
	v_readlane_b32 s40, v238, 28
	global_load_dwordx2 v[100:101], v[4:5], off
	global_load_dwordx4 v[14:17], v[6:7], off
	global_load_dwordx2 v[98:99], v[4:5], off offset:32
	global_load_dwordx4 v[10:13], v[6:7], off offset:64
	global_load_dwordx2 v[96:97], v[4:5], off offset:64
	s_nop 0
	global_load_dwordx4 v[6:9], v[6:7], off offset:128
	v_readlane_b32 s41, v238, 29
	global_load_dwordx2 v[94:95], v[2:3], off
	v_lshl_add_u64 v[2:3], v[82:83], 2, s[14:15]
	s_mul_i32 s14, s40, 0x2a00
	s_add_u32 s14, s4, s14
	s_mul_hi_i32 s15, s40, 0x2a00
	s_addc_u32 s15, s5, s15
	v_mov_b64_e32 v[24:25], s[14:15]
	v_mad_i64_i32 v[24:25], s[22:23], v128, s59, v[24:25]
	v_lshl_add_u64 v[24:25], v[24:25], 0, s[18:19]
	v_readlane_b32 s18, v238, 30
	v_lshl_add_u64 v[84:85], s[14:15], 0, v[84:85]
	v_readlane_b32 s19, v238, 31
	s_add_u32 s18, s24, s18
	v_lshl_add_u64 v[84:85], v[84:85], 0, s[2:3]
	s_addc_u32 s19, s25, s19
	s_lshl_b64 s[22:23], s[40:41], 1
	v_lshl_add_u64 v[84:85], v[84:85], 0, s[64:65]
	s_add_u32 s22, s8, s22
	v_lshl_add_u64 v[86:87], v[84:85], 0, v[86:87]
	v_lshl_add_u64 v[84:85], v[84:85], 0, v[106:107]
	s_waitcnt vmcnt(0)
	v_mul_f32_e32 v106, 0x3fb8aa3b, v78
	v_mul_f32_e32 v78, 0xbfb8aa3b, v78
	v_mul_f32_e32 v107, 0x3fb8aa3b, v79
	v_mul_f32_e32 v79, 0xbfb8aa3b, v79
	s_addc_u32 s23, s9, s23
	v_exp_f32_e32 v106, v106
	v_exp_f32_e32 v78, v78
	v_exp_f32_e32 v107, v107
	v_exp_f32_e32 v79, v79
	v_lshl_add_u64 v[26:27], s[22:23], 0, v[18:19]
	v_lshl_add_u64 v[24:25], v[24:25], 0, v[18:19]
	v_lshl_add_u64 v[36:37], s[18:19], 0, v[18:19]
	v_mad_i64_i32 v[18:19], s[18:19], v28, s6, v[26:27]
	v_mad_i64_i32 v[26:27], s[18:19], v29, s6, v[26:27]
	v_lshlrev_b32_e32 v108, 16, v66
	v_and_b32_e32 v109, 0xffff0000, v66
	s_mov_b32 s6, 0x3e000000
	v_pk_mul_f32 v[108:109], v[108:109], s[6:7] op_sel_hi:[1,0]
	v_lshlrev_b32_e32 v112, 16, v54
	v_and_b32_e32 v113, 0xffff0000, v54
	v_mul_f32_e32 v54, 0x3fb8aa3b, v80
	v_pk_mul_f32 v[110:111], v[108:109], v[106:107]
	v_pk_mul_f32 v[108:109], v[108:109], v[78:79]
	v_pk_mul_f32 v[106:107], v[106:107], v[112:113]
	v_pk_mul_f32 v[78:79], v[78:79], v[112:113]
	v_exp_f32_e32 v112, v54
	v_mul_f32_e32 v54, 0xbfb8aa3b, v80
	v_exp_f32_e32 v80, v54
	v_mul_f32_e32 v54, 0x3fb8aa3b, v81
	v_exp_f32_e32 v113, v54
	v_mul_f32_e32 v54, 0xbfb8aa3b, v81
	v_exp_f32_e32 v81, v54
	v_lshlrev_b32_e32 v66, 16, v67
	v_and_b32_e32 v67, 0xffff0000, v67
	v_pk_mul_f32 v[66:67], v[66:67], s[6:7] op_sel_hi:[1,0]
	v_lshlrev_b32_e32 v54, 16, v55
	v_and_b32_e32 v55, 0xffff0000, v55
	v_pk_mul_f32 v[114:115], v[66:67], v[112:113]
	v_pk_mul_f32 v[66:67], v[66:67], v[80:81]
	v_pk_mul_f32 v[112:113], v[112:113], v[54:55]
	v_pk_mul_f32 v[80:81], v[80:81], v[54:55]
	v_mul_f32_e32 v55, 0xbfb8aa3b, v74
	v_mul_f32_e32 v54, 0x3fb8aa3b, v74
	v_exp_f32_e32 v74, v55
	v_mul_f32_e32 v55, 0x3fb8aa3b, v75
	v_exp_f32_e32 v54, v54
	v_exp_f32_e32 v55, v55
	v_mul_f32_e32 v75, 0xbfb8aa3b, v75
	v_exp_f32_e32 v75, v75
	v_lshlrev_b32_e32 v116, 16, v68
	v_and_b32_e32 v117, 0xffff0000, v68
	v_pk_mul_f32 v[116:117], v[116:117], s[6:7] op_sel_hi:[1,0]
	v_lshlrev_b32_e32 v120, 16, v56
	v_and_b32_e32 v121, 0xffff0000, v56
	v_pk_mul_f32 v[118:119], v[116:117], v[54:55]
	v_pk_mul_f32 v[122:123], v[54:55], v[120:121]
	v_mul_f32_e32 v55, 0xbfb8aa3b, v76
	v_pk_mul_f32 v[116:117], v[116:117], v[74:75]
	v_pk_mul_f32 v[120:121], v[74:75], v[120:121]
	v_mul_f32_e32 v54, 0x3fb8aa3b, v76
	v_exp_f32_e32 v74, v55
	v_mul_f32_e32 v55, 0x3fb8aa3b, v77
	v_add_co_u32_e32 v24, vcc, s61, v24
	v_exp_f32_e32 v54, v54
	v_exp_f32_e32 v55, v55
	v_mul_f32_e32 v56, 0xbfb8aa3b, v77
	v_addc_co_u32_e32 v25, vcc, 0, v25, vcc
	v_exp_f32_e32 v75, v56
	global_load_dwordx4 v[2:5], v[2:3], off
	s_nop 0
	global_load_dwordx4 v[38:41], v[24:25], off offset:2048 nt
	global_load_dwordx4 v[30:33], v[24:25], off offset:2560 nt
	v_add_u32_e32 v24, s40, v128
	v_lshlrev_b32_e32 v68, 16, v69
	v_and_b32_e32 v69, 0xffff0000, v69
	v_ashrrev_i32_e32 v25, 31, v24
	v_pk_mul_f32 v[68:69], v[68:69], s[6:7] op_sel_hi:[1,0]
	v_lshlrev_b32_e32 v56, 16, v57
	v_and_b32_e32 v57, 0xffff0000, v57
	v_lshlrev_b64 v[24:25], 10, v[24:25]
	v_pk_mul_f32 v[76:77], v[68:69], v[54:55]
	v_pk_mul_f32 v[124:125], v[54:55], v[56:57]
	s_movk_i32 s6, 0x90
	v_lshlrev_b32_e32 v54, 4, v104
	v_lshl_add_u64 v[24:25], s[36:37], 0, v[24:25]
	v_pk_mul_f32 v[68:69], v[68:69], v[74:75]
	v_pk_mul_f32 v[126:127], v[74:75], v[56:57]
	v_mul_lo_u32 v128, v128, s6
	v_and_b32_e32 v75, 0x70, v54
	v_lshl_add_u64 v[24:25], v[24:25], 0, s[38:39]
	v_add_u32_e32 v74, v128, v75
	v_lshl_add_u64 v[20:21], v[24:25], 0, v[20:21]
	v_lshl_add_u64 v[22:23], v[36:37], 0, v[22:23]
	v_lshl_add_u64 v[34:35], v[36:37], 0, v[34:35]
	v_cvt_pk_bf16_f32 v54, v110, v111
	v_cvt_pk_bf16_f32 v55, v114, v115
	v_cvt_pk_bf16_f32 v56, v118, v119
	v_cvt_pk_bf16_f32 v57, v76, v77
	v_add_u32_e32 v74, 0, v74
	global_load_dwordx4 v[42:45], v[20:21], off offset:16 nt
	global_load_dwordx4 v[46:49], v[20:21], off nt
	v_readlane_b32 s7, v236, 32
	global_load_dwordx4 v[18:21], v[18:19], off nt
	v_readlane_b32 s18, v236, 33
	global_load_dwordx4 v[22:25], v[22:23], off nt
	s_lshl_b32 s14, s78, 3
	global_load_dwordx4 v[26:29], v[26:27], off nt
	s_and_b32 s14, s14, -16
	global_load_dwordx4 v[34:37], v[34:35], off nt
	s_nop 0
	global_load_dwordx2 v[92:93], v[86:87], off
	global_load_dwordx2 v[88:89], v[86:87], off offset:32
	s_nop 0
	global_load_dwordx2 v[86:87], v[86:87], off offset:64
	ds_write_b128 v74, v[54:57] offset:27648
	v_cvt_pk_bf16_f32 v54, v108, v109
	v_cvt_pk_bf16_f32 v55, v66, v67
	v_cvt_pk_bf16_f32 v56, v116, v117
	v_cvt_pk_bf16_f32 v57, v68, v69
	ds_write_b128 v74, v[54:57] offset:36864
	v_cvt_pk_bf16_f32 v54, v106, v107
	v_cvt_pk_bf16_f32 v55, v112, v113
	v_cvt_pk_bf16_f32 v56, v122, v123
	v_cvt_pk_bf16_f32 v57, v124, v125
	ds_write_b128 v74, v[54:57] offset:46080
	v_cvt_pk_bf16_f32 v54, v78, v79
	v_cvt_pk_bf16_f32 v55, v80, v81
	v_cvt_pk_bf16_f32 v56, v120, v121
	v_cvt_pk_bf16_f32 v57, v126, v127
	ds_write_b128 v74, v[54:57] offset:55296
	v_add_u32_e32 v54, s7, v75
	v_add_u32_e32 v55, s18, v75
	v_add_u32_e32 v75, v54, v128
	ds_write_b128 v75, v[50:53]
	v_mul_lo_u32 v50, v129, s6
	v_add_u32_e32 v77, v54, v50
	v_add_u32_e32 v78, v55, v50
	v_or_b32_e32 v50, s14, v102
	v_mul_lo_u32 v50, v50, s6
	v_add_u32_e32 v76, v55, v128
	v_add_u32_e32 v50, 0, v50
	v_lshlrev_b32_e32 v67, 4, v103
	s_lshl_b32 s15, s78, 5
	ds_write_b128 v76, v[58:61]
	ds_write_b128 v78, v[70:73]
	v_add_u32_e32 v69, v50, v67
	v_add_u32_e32 v70, 0, v67
	v_and_or_b32 v66, s15, 32, v102
	global_load_dwordx2 v[84:85], v[84:85], off
	ds_write_b128 v77, v[62:65]
	s_waitcnt lgkmcnt(0)
	s_barrier
	v_mad_u32_u24 v72, v66, s6, v70
	ds_read_b128 v[50:53], v69 offset:27648
	ds_read_b128 v[54:57], v72 offset:55296
	s_waitcnt lgkmcnt(0)
	v_mfma_f32_16x16x32_bf16 v[50:53], v[50:53], v[54:57], 0
	ds_read_b128 v[54:57], v69 offset:36864
	ds_read_b128 v[58:61], v72 offset:46080
	v_or_b32_e32 v68, s14, v0
	s_add_i32 s14, 0, 0x12000
	s_waitcnt lgkmcnt(0)
	v_mfma_f32_16x16x32_bf16 v[54:57], v[54:57], v[58:61], 0
	ds_read_b128 v[58:61], v69 offset:27712
	ds_read_b128 v[62:65], v72 offset:55360
	v_cmp_gt_i32_e64 s[38:39], v66, v68
	v_mul_lo_u32 v79, v68, s6
	s_waitcnt lgkmcnt(0)
	v_mfma_f32_16x16x32_bf16 v[50:53], v[58:61], v[62:65], v[50:53]
	ds_read_b128 v[58:61], v69 offset:36928
	ds_read_b128 v[62:65], v72 offset:46144
	v_or_b32_e32 v80, 1, v68
	v_cmp_gt_i32_e64 s[40:41], v66, v80
	s_waitcnt lgkmcnt(0)
	v_mfma_f32_16x16x32_bf16 v[54:57], v[58:61], v[62:65], v[54:57]
	v_lshl_add_u32 v58, v66, 1, s14
	v_add_u32_e32 v71, v58, v79
	v_readlane_b32 s42, v236, 13
	s_nop 4
	v_cndmask_b32_e64 v50, v50, v54, s[38:39]
	v_cvt_pk_bf16_f32 v50, v50, s0
	v_readlane_b32 s43, v236, 14
	ds_write_b16 v71, v50
	v_cndmask_b32_e64 v50, v51, v55, s[40:41]
	v_add_u32_e32 v81, 0x90, v79
	v_or_b32_e32 v104, 2, v68
	v_cvt_pk_bf16_f32 v50, v50, s0
	v_add_u32_e32 v51, v58, v81
	v_cmp_gt_i32_e64 s[42:43], v66, v104
	v_readlane_b32 s44, v236, 15
	v_readlane_b32 s45, v236, 16
	ds_write_b16 v51, v50
	v_cndmask_b32_e64 v50, v52, v56, s[42:43]
	v_add_u32_e32 v106, 0x120, v79
	v_or_b32_e32 v107, 3, v68
	v_cvt_pk_bf16_f32 v50, v50, s0
	v_add_u32_e32 v51, v58, v106
	v_cmp_gt_i32_e64 s[44:45], v66, v107
	ds_write_b16 v51, v50
	v_add_u32_e32 v108, 0x1b0, v79
	v_cndmask_b32_e64 v50, v53, v57, s[44:45]
	v_cvt_pk_bf16_f32 v50, v50, s0
	v_add_u32_e32 v51, v58, v108
	ds_write_b16 v51, v50
	ds_read_b128 v[50:53], v69 offset:27648
	ds_read_b128 v[54:57], v72 offset:57600
	s_waitcnt lgkmcnt(0)
	v_mfma_f32_16x16x32_bf16 v[50:53], v[50:53], v[54:57], 0
	ds_read_b128 v[54:57], v69 offset:36864
	ds_read_b128 v[58:61], v72 offset:48384
	v_readlane_b32 s46, v236, 17
	v_readlane_b32 s47, v236, 18
	s_waitcnt lgkmcnt(0)
	v_mfma_f32_16x16x32_bf16 v[54:57], v[54:57], v[58:61], 0
	ds_read_b128 v[58:61], v69 offset:27712
	ds_read_b128 v[62:65], v72 offset:57664
	v_or_b32_e32 v109, 16, v66
	v_cmp_gt_i32_e64 s[46:47], v109, v68
	s_waitcnt lgkmcnt(0)
	v_mfma_f32_16x16x32_bf16 v[50:53], v[58:61], v[62:65], v[50:53]
	ds_read_b128 v[58:61], v69 offset:36928
	ds_read_b128 v[62:65], v72 offset:48448
	v_readlane_b32 s48, v236, 19
	v_readlane_b32 s49, v236, 20
	s_waitcnt lgkmcnt(0)
	v_mfma_f32_16x16x32_bf16 v[54:57], v[58:61], v[62:65], v[54:57]
	v_cmp_gt_i32_e64 s[48:49], v109, v80
	v_readlane_b32 s50, v236, 21
	v_readlane_b32 s51, v236, 22
	s_nop 4
	v_cndmask_b32_e64 v50, v50, v54, s[46:47]
	v_lshlrev_b32_e32 v54, 1, v109
	v_cvt_pk_bf16_f32 v50, v50, s0
	v_add3_u32 v79, s14, v79, v54
	ds_write_b16 v79, v50
	v_cndmask_b32_e64 v50, v51, v55, s[48:49]
	v_cvt_pk_bf16_f32 v50, v50, s0
	v_add3_u32 v81, s14, v81, v54
	v_cmp_gt_i32_e64 s[50:51], v109, v104
	ds_write_b16 v81, v50
	v_add3_u32 v104, s14, v106, v54
	v_cndmask_b32_e64 v50, v52, v56, s[50:51]
	v_cvt_pk_bf16_f32 v50, v50, s0
	v_cmp_gt_i32_e64 s[52:53], v109, v107
	ds_write_b16 v104, v50
	v_mov_b32_e32 v73, s14
	v_cndmask_b32_e64 v50, v53, v57, s[52:53]
	v_cvt_pk_bf16_f32 v50, v50, s0
	v_add3_u32 v106, s14, v108, v54
	ds_write_b16 v106, v50
	v_mad_u32_u24 v50, v105, s6, v73
	v_add_u32_e32 v73, v50, v67
	v_mad_u32_u24 v50, v105, s6, 0
	v_or_b32_e32 v110, s0, v102
	v_add_u32_e32 v72, v50, v67
	v_add_u32_e32 v68, s7, v67
	v_mul_lo_u32 v50, v110, s6
	v_add_u32_e32 v67, s18, v67
	v_add_u32_e32 v107, v68, v50
	s_waitcnt lgkmcnt(0)
	s_barrier
	v_add_u32_e32 v80, v67, v50
	ds_read_b128 v[50:53], v107
	ds_read_b128 v[114:117], v73
	ds_read_b128 v[54:57], v80
	ds_read_b128 v[118:121], v72 offset:27648
	s_waitcnt lgkmcnt(2)
	v_mfma_f32_16x16x32_bf16 v[50:53], v[50:53], v[114:117], 0
	v_readlane_b32 s54, v236, 25
	v_readlane_b32 s55, v236, 26
	v_cmp_eq_u32_e64 s[54:55], 0, v103
	s_waitcnt lgkmcnt(0)
	v_mfma_f32_16x16x32_bf16 v[50:53], v[54:57], v[118:121], v[50:53]
	ds_read_b128 v[54:57], v107 offset:64
	ds_read_b128 v[122:125], v73 offset:64
	s_waitcnt lgkmcnt(0)
	v_mfma_f32_16x16x32_bf16 v[50:53], v[54:57], v[122:125], v[50:53]
	ds_read_b128 v[54:57], v80 offset:64
	ds_read_b128 v[126:129], v72 offset:27712
	s_waitcnt lgkmcnt(0)
	v_mfma_f32_16x16x32_bf16 v[62:65], v[54:57], v[126:129], v[50:53]
	s_nop 3
	v_or_b32_e32 v50, 16, v110
	v_mul_lo_u32 v50, v50, s6
	v_add_u32_e32 v109, v68, v50
	v_add_u32_e32 v108, v67, v50
	ds_read_b128 v[50:53], v109
	ds_read_b128 v[54:57], v108
	s_waitcnt lgkmcnt(1)
	v_mfma_f32_16x16x32_bf16 v[50:53], v[50:53], v[114:117], 0
	s_waitcnt lgkmcnt(0)
	v_mfma_f32_16x16x32_bf16 v[50:53], v[54:57], v[118:121], v[50:53]
	ds_read_b128 v[54:57], v109 offset:64
	s_waitcnt lgkmcnt(0)
	v_mfma_f32_16x16x32_bf16 v[50:53], v[54:57], v[122:125], v[50:53]
	ds_read_b128 v[54:57], v108 offset:64
	s_waitcnt lgkmcnt(0)
	v_mfma_f32_16x16x32_bf16 v[58:61], v[54:57], v[126:129], v[50:53]
	s_nop 4
	v_or_b32_e32 v50, 32, v110
	v_mul_lo_u32 v50, v50, s6
	v_add_u32_e32 v111, v68, v50
	v_add_u32_e32 v110, v67, v50
	ds_read_b128 v[50:53], v111
	ds_read_b128 v[54:57], v110
	s_waitcnt lgkmcnt(1)
	v_mfma_f32_16x16x32_bf16 v[50:53], v[50:53], v[114:117], 0
	s_waitcnt lgkmcnt(0)
	v_mfma_f32_16x16x32_bf16 v[50:53], v[54:57], v[118:121], v[50:53]
	ds_read_b128 v[54:57], v111 offset:64
	s_waitcnt lgkmcnt(0)
	v_mfma_f32_16x16x32_bf16 v[50:53], v[54:57], v[122:125], v[50:53]
	ds_read_b128 v[54:57], v110 offset:64
	s_waitcnt lgkmcnt(0)
	v_mfma_f32_16x16x32_bf16 v[54:57], v[54:57], v[126:129], v[50:53]
	s_nop 4
	v_or_b32_e32 v50, s1, v102
	v_mul_lo_u32 v50, v50, s6
	v_add_u32_e32 v113, v68, v50
	v_add_u32_e32 v112, v67, v50
	ds_read_b128 v[50:53], v113
	s_waitcnt lgkmcnt(0)
	v_mfma_f32_16x16x32_bf16 v[50:53], v[50:53], v[114:117], 0
	ds_read_b128 v[114:117], v112
	v_mul_f32_e32 v67, v63, v63
	v_mul_f32_e32 v68, v65, v65
	s_waitcnt lgkmcnt(0)
	v_mfma_f32_16x16x32_bf16 v[50:53], v[114:117], v[118:121], v[50:53]
	ds_read_b128 v[114:117], v113 offset:64
	v_fmac_f32_e32 v67, v62, v62
	v_fmac_f32_e32 v68, v64, v64
	s_waitcnt lgkmcnt(0)
	v_mfma_f32_16x16x32_bf16 v[50:53], v[114:117], v[122:125], v[50:53]
	ds_read_b128 v[114:117], v112 offset:64
	v_add_f32_e32 v67, v67, v68
	v_mul_f32_e32 v68, v59, v59
	s_waitcnt lgkmcnt(0)
	v_mfma_f32_16x16x32_bf16 v[50:53], v[114:117], v[126:129], v[50:53]
	v_mul_f32_e32 v114, v61, v61
	v_fmac_f32_e32 v68, v58, v58
	v_fmac_f32_e32 v114, v60, v60
	v_add_f32_e32 v68, v68, v114
	v_add_f32_e32 v67, v67, v68
	v_mul_f32_e32 v68, v55, v55
	v_mul_f32_e32 v114, v57, v57
	v_fmac_f32_e32 v68, v54, v54
	v_fmac_f32_e32 v114, v56, v56
	v_add_f32_e32 v68, v68, v114
	v_add_f32_e32 v67, v67, v68
	v_mul_f32_e32 v68, v51, v51
	v_mul_f32_e32 v114, v53, v53
	v_fmac_f32_e32 v68, v50, v50
	v_fmac_f32_e32 v114, v52, v52
	v_add_f32_e32 v68, v68, v114
	v_and_b32_e32 v114, 64, v209
	v_add_f32_e32 v67, v67, v68
	v_xor_b32_e32 v68, 16, v209
	v_add_u32_e32 v115, 64, v114
	v_cmp_lt_i32_e32 vcc, v68, v115
	s_nop 1
	v_cndmask_b32_e32 v68, v209, v68, vcc
	v_lshlrev_b32_e32 v114, 2, v68
	v_mov_b32_e32 v68, v67
	s_nop 1
	v_permlane16_swap_b32_e32 v68, v67
	s_waitcnt lgkmcnt(0)
	v_add_f32_e32 v67, v67, v68
	v_xor_b32_e32 v68, 32, v209
	v_cmp_lt_i32_e32 vcc, v68, v115
	s_nop 1
	v_cndmask_b32_e32 v68, v209, v68, vcc
	v_lshlrev_b32_e32 v115, 2, v68
	v_mov_b32_e32 v68, v67
	s_nop 1
	v_permlane32_swap_b32_e32 v68, v67
	s_and_saveexec_b64 s[18:19], s[54:55]
	s_cbranch_execz .LBB0_354
	s_and_b32 s1, s77, 0xffffff00
	s_add_i32 s1, s1, 0
	s_lshl_b32 s14, s79, 2
	s_add_i32 s1, s1, s14
	s_waitcnt lgkmcnt(0)
	v_add_f32_e32 v67, v67, v68
	v_lshl_add_u32 v68, v102, 2, s1
	ds_write_b32 v68, v67 offset:27136

.LBB0_377:
	s_ashr_i32 s39, s40, 2
	s_bfe_u32 s15, s15, 0x20006
	s_lshl_b32 s0, s23, 7
	s_ashr_i32 s1, s0, 31
	s_mul_i32 s24, s23, 0x204000
	s_lshl_b32 s38, s39, 7
	s_lshl_b32 s23, s15, 5
	s_mul_hi_i32 s25, s0, 0x4080
	s_or_b32 s18, s23, s38
	s_lshl_b64 s[0:1], s[0:1], 1
	v_bfe_u32 v7, v8, 4, 2
	s_add_u32 s36, s4, s0
	v_and_b32_e32 v6, 15, v8
	s_addc_u32 s37, s5, s1
	v_lshlrev_b32_e32 v2, 4, v7
	v_mov_b32_e32 v3, v1
	v_or_b32_e32 v192, s18, v6
	v_lshl_add_u64 v[14:15], s[36:37], 0, v[2:3]
	v_mad_i64_i32 v[4:5], s[18:19], v192, s59, v[14:15]
	s_add_u32 s18, s8, s24
	s_addc_u32 s19, s9, s25
	s_lshl_b32 s24, s39, 1
	s_sub_i32 s25, 8, s24
	s_max_i32 s25, s25, 0
	s_add_i32 s24, s24, s25
	s_lshl_b32 s24, s24, 6
	s_add_i32 s42, s24, 0xfffffe00
	v_lshlrev_b32_e32 v24, 4, v8
	v_and_b32_e32 v16, 0xf0, v24
	v_mov_b32_e32 v17, v1
	s_ashr_i32 s43, s42, 31
	v_lshlrev_b32_e32 v0, 3, v8
	v_lshl_add_u64 v[194:195], s[36:37], 0, v[16:17]
	s_lshl_b64 s[36:37], s[42:43], 1
	s_add_u32 s36, s18, s36
	v_and_b32_e32 v0, 56, v0
	global_load_dwordx4 v[66:69], v[4:5], off
	global_load_dwordx4 v[70:73], v[4:5], off offset:64
	global_load_dwordx4 v[74:77], v[4:5], off offset:128
	global_load_dwordx4 v[78:81], v[4:5], off offset:192
	s_addc_u32 s37, s19, s37
	v_lshlrev_b32_e32 v4, 1, v0
	v_mov_b32_e32 v5, v1
	v_lshrrev_b32_sdwa v3, v211, v8 dst_sel:DWORD dst_unused:UNUSED_PAD src0_sel:DWORD src1_sel:BYTE_0
	v_lshl_add_u64 v[18:19], s[36:37], 0, v[4:5]
	v_or_b32_e32 v0, s42, v3
	v_lshrrev_b32_sdwa v5, v212, v8 dst_sel:DWORD dst_unused:UNUSED_PAD src0_sel:DWORD src1_sel:BYTE_0
	v_mad_i64_i32 v[10:11], s[36:37], v0, s59, v[194:195]
	v_mul_u32_u24_e32 v0, 0x2040, v5
	v_lshlrev_b32_e32 v0, 1, v0
	s_movk_i32 s24, 0x100
	v_lshl_add_u64 v[12:13], v[18:19], 0, v[0:1]
	global_load_dwordx4 v[86:89], v[10:11], off offset:2048
	global_load_dwordx4 v[90:93], v[12:13], off
	v_or_b32_sdwa v10, v8, s24 dst_sel:DWORD dst_unused:UNUSED_PAD src0_sel:BYTE_0 src1_sel:DWORD
	v_lshrrev_b32_e32 v9, 4, v10
	v_or_b32_e32 v11, s42, v9
	v_mad_i64_i32 v[12:13], s[36:37], v11, s59, v[194:195]
	v_lshrrev_b32_e32 v11, 3, v10
	v_mul_u32_u24_e32 v10, 0x2040, v11
	v_lshlrev_b32_e32 v196, 1, v10
	v_mov_b32_e32 v197, v1
	s_movk_i32 s24, 0x200
	v_lshl_add_u64 v[20:21], v[18:19], 0, v[196:197]
	global_load_dwordx4 v[94:97], v[12:13], off offset:2048
	global_load_dwordx4 v[98:101], v[20:21], off
	v_or_b32_sdwa v12, v8, s24 dst_sel:DWORD dst_unused:UNUSED_PAD src0_sel:BYTE_0 src1_sel:DWORD
	v_lshrrev_b32_e32 v10, 4, v12
	v_or_b32_e32 v13, s42, v10
	v_lshrrev_b32_e32 v12, 3, v12
	v_mad_i64_i32 v[20:21], s[36:37], v13, s59, v[194:195]
	v_mul_u32_u24_e32 v13, 0x2040, v12
	s_movk_i32 s24, 0x300
	v_lshlrev_b32_e32 v198, 1, v13
	v_or_b32_sdwa v13, v8, s24 dst_sel:DWORD dst_unused:UNUSED_PAD src0_sel:BYTE_0 src1_sel:DWORD
	v_lshrrev_b32_e32 v8, 4, v13
	v_mov_b32_e32 v199, v1
	v_or_b32_e32 v17, s42, v8
	v_lshrrev_b32_e32 v13, 3, v13
	v_lshl_add_u64 v[22:23], v[18:19], 0, v[198:199]
	global_load_dwordx4 v[118:121], v[20:21], off offset:2048
	global_load_dwordx4 v[122:125], v[22:23], off
	v_mad_i64_i32 v[20:21], s[36:37], v17, s59, v[194:195]
	v_mul_u32_u24_e32 v17, 0x2040, v13
	v_lshlrev_b32_e32 v200, 1, v17
	v_mov_b32_e32 v201, v1
	v_or_b32_e32 v190, 16, v192
	v_lshl_add_u64 v[18:19], v[18:19], 0, v[200:201]
	v_mad_i64_i32 v[14:15], s[36:37], v190, s59, v[14:15]
	global_load_dwordx4 v[130:133], v[20:21], off offset:2048
	global_load_dwordx4 v[134:137], v[18:19], off
	global_load_dwordx4 v[102:105], v[14:15], off
	global_load_dwordx4 v[106:109], v[14:15], off offset:64
	global_load_dwordx4 v[110:113], v[14:15], off offset:128
	global_load_dwordx4 v[114:117], v[14:15], off offset:192
	s_mul_i32 s22, s22, 0x11800
	s_add_i32 s24, s22, 0
	v_add_u32_e32 v191, s24, v16
	v_and_b32_e32 v14, 0x70, v24
	s_movk_i32 s7, 0x110
	v_add_u32_e32 v193, s24, v14
	v_mad_u32_u24 v14, v3, s7, v191
	s_movk_i32 s6, 0x90
	s_mov_b64 s[36:37], -1
	s_cmp_gt_i32 s39, -1
	v_lshlrev_b32_e32 v216, 2, v7
	s_waitcnt vmcnt(0)
	v_mul_f32_e32 v244, 0x3fb8aa3b, v244
	ds_write_b32 v245, v244
	v_mul_f32_e32 v246, 0x3fb8aa3b, v246
	v_mov_b32_e32 v247, s14
	ds_write_b32 v247, v246 offset:1024
	ds_write_b128 v14, v[86:89]
	v_mad_u32_u24 v14, v5, s6, v193
	ds_write_b128 v14, v[90:93] offset:34816
	v_mad_u32_u24 v14, v9, s7, v191
	ds_write_b128 v14, v[94:97]
	v_mad_u32_u24 v14, v11, s6, v193
	ds_write_b128 v14, v[98:101] offset:34816
	v_mad_u32_u24 v14, v10, s7, v191
	ds_write_b128 v14, v[118:121]
	v_mad_u32_u24 v14, v12, s6, v193
	ds_write_b128 v14, v[122:125] offset:34816
	v_mad_u32_u24 v14, v8, s7, v191
	ds_write_b128 v14, v[130:133]
	v_mad_u32_u24 v14, v13, s6, v193
	ds_write_b128 v14, v[134:137] offset:34816
	s_waitcnt lgkmcnt(0)
	s_barrier
	s_cbranch_scc1 .LBB0_379
	v_lshlrev_b32_e32 v138, 2, v7
	s_mov_b64 s[36:37], 0

.Lband_exit:
	v_mov_b32_e32 v138, v216
	v_lshlrev_b32_e32 v125, 1, v138
	v_mad_u32_u24 v122, v192, s59, v125
	v_lshl_add_u32 v124, v192, 12, v125
	s_add_u32 s14, s4, s0
	s_addc_u32 s15, s5, s1
	s_add_u32 s14, s14, 0x1000
	s_addc_u32 s15, s15, 0
	s_add_u32 s38, s56, s0
	s_addc_u32 s39, s57, s1
	v_add_u32_e32 v123, 0x2a000, v122
	v_add_u32_e32 v125, 0x10000, v124
	global_load_dwordx2 v[86:87], v122, s[14:15]
	global_load_dwordx2 v[88:89], v122, s[14:15] offset:32
	global_load_dwordx2 v[90:91], v122, s[14:15] offset:64
	global_load_dwordx2 v[92:93], v122, s[14:15] offset:96
	global_load_dwordx2 v[94:95], v122, s[14:15] offset:128
	global_load_dwordx2 v[96:97], v122, s[14:15] offset:160
	global_load_dwordx2 v[98:99], v122, s[14:15] offset:192
	global_load_dwordx2 v[100:101], v122, s[14:15] offset:224
	global_load_dwordx2 v[102:103], v123, s[14:15]
	global_load_dwordx2 v[104:105], v123, s[14:15] offset:32
	global_load_dwordx2 v[106:107], v123, s[14:15] offset:64
	global_load_dwordx2 v[108:109], v123, s[14:15] offset:96
	global_load_dwordx2 v[110:111], v123, s[14:15] offset:128
	global_load_dwordx2 v[112:113], v123, s[14:15] offset:160
	global_load_dwordx2 v[114:115], v123, s[14:15] offset:192
	global_load_dwordx2 v[116:117], v123, s[14:15] offset:224
	s_barrier
	s_branch .Lband_epi_compute

.LBB0_403:
	s_and_b32 s18, s44, 0x180
	s_and_b32 s24, s45, 0xffffff80
	s_lshl_b32 s47, s18, 1
	s_add_u32 s14, s2, s47
	s_addc_u32 s15, s36, 0
	s_add_u32 s22, s1, s47
	s_addc_u32 s23, s37, 0
	s_or_b32 s18, s18, s0
	s_ashr_i32 s19, s18, 31
	s_lshl_b64 s[18:19], s[18:19], 9
	v_mov_b32_e32 v0, v204
	s_add_u32 s18, s38, s18
	s_addc_u32 s19, s39, s19
	v_lshlrev_b32_e32 v4, 4, v0
	v_ashrrev_i32_e32 v12, 4, v0
	v_ashrrev_i32_e32 v14, 3, v0
	v_and_b32_e32 v10, 0xf0, v4
	v_mov_b32_e32 v11, v1
	v_and_b32_e32 v18, 0x70, v4
	v_mov_b32_e32 v19, v1
	v_ashrrev_i32_e32 v13, 31, v12
	v_ashrrev_i32_e32 v15, 31, v14
	v_add_u32_e32 v8, 0x200, v0
	v_lshl_add_u64 v[2:3], s[22:23], 0, v[10:11]
	v_lshl_add_u64 v[4:5], s[18:19], 0, v[18:19]
	v_lshlrev_b64 v[6:7], 12, v[12:13]
	v_lshlrev_b64 v[20:21], 9, v[14:15]
	v_ashrrev_i32_e32 v16, 4, v8
	v_lshl_add_u64 v[54:55], v[2:3], 0, v[6:7]
	v_lshl_add_u64 v[6:7], v[4:5], 0, v[20:21]
	v_ashrrev_i32_e32 v17, 31, v16
	v_ashrrev_i32_e32 v22, 3, v8
	global_load_dwordx4 v[34:37], v[54:55], off
	global_load_dwordx4 v[38:41], v[6:7], off
	v_lshlrev_b64 v[6:7], 12, v[16:17]
	v_ashrrev_i32_e32 v23, 31, v22
	v_lshl_add_u64 v[56:57], v[2:3], 0, v[6:7]
	v_lshlrev_b64 v[24:25], 9, v[22:23]
	v_readfirstlane_b32 s22, v0
	v_lshl_add_u64 v[2:3], v[4:5], 0, v[24:25]
	global_load_dwordx4 v[42:45], v[56:57], off
	global_load_dwordx4 v[46:49], v[2:3], off
	v_and_b32_e32 v66, 15, v0
	s_ashr_i32 s22, s22, 2
	v_bfe_u32 v67, v0, 4, 2
	s_and_b32 s22, s22, -16
	v_or_b32_e32 v0, s24, v66
	v_add_u32_e32 v90, s22, v0
	v_mov_b64_e32 v[2:3], s[14:15]
	v_mad_i64_i32 v[2:3], s[14:15], v90, s59, v[2:3]
	v_lshlrev_b32_e32 v0, 4, v67
	v_lshl_add_u64 v[26:27], v[2:3], 0, v[0:1]
	global_load_dwordx4 v[6:9], v[26:27], off
	global_load_dwordx4 v[2:5], v[26:27], off offset:64
	s_movk_i32 s7, 0x110
	v_mul_lo_u32 v15, v12, s7
	v_add_u32_e32 v23, 0, v10
	global_load_dwordx4 v[10:13], v[26:27], off offset:128
	s_movk_i32 s6, 0x90
	v_mul_lo_u32 v14, v14, s6
	v_mad_u32_u24 v17, v66, s7, 0
	v_add_u32_e32 v28, 0, v18
	v_mul_lo_u32 v16, v16, s7
	v_add_u32_e32 v143, v17, v0
	v_add_u32_e32 v145, v23, v15
	v_add_u32_e32 v147, v28, v14
	v_add_u32_e32 v149, v23, v16
	global_load_dwordx4 v[14:17], v[26:27], off offset:192
	v_mul_lo_u32 v22, v22, s6
	s_mov_b32 s6, 0x40000
	v_add_u32_e32 v151, v28, v22
	v_add_co_u32_e32 v22, vcc, s6, v54
	v_lshl_add_u64 v[20:21], s[18:19], 0, v[20:21]
	s_nop 0
	v_addc_co_u32_e32 v23, vcc, 0, v55, vcc
	v_add_co_u32_e32 v26, vcc, s6, v56
	v_lshl_add_u64 v[24:25], s[18:19], 0, v[24:25]
	s_nop 0
	v_addc_co_u32_e32 v27, vcc, 0, v57, vcc
	v_lshl_add_u64 v[70:71], v[20:21], 0, v[18:19]
	v_lshl_add_u64 v[72:73], v[24:25], 0, v[18:19]
	global_load_dwordx4 v[18:21], v[22:23], off
	s_nop 0
	global_load_dwordx4 v[22:25], v[70:71], off offset:128
	s_nop 0
	global_load_dwordx4 v[26:29], v[26:27], off
	s_nop 0
	global_load_dwordx4 v[30:33], v[72:73], off offset:128
	v_xor_b32_e32 v0, 16, v209
	v_lshlrev_b32_e32 v92, 3, v67
	s_mov_b32 s14, 0xf149f2ca
	s_mov_b32 s6, 0x80000
	s_waitcnt vmcnt(11)
	ds_write_b128 v145, v[34:37]
	s_waitcnt vmcnt(10)
	ds_write_b128 v147, v[38:41] offset:34816
	s_waitcnt vmcnt(9)
	ds_write_b128 v149, v[42:45]
	s_waitcnt vmcnt(8)
	ds_write_b128 v151, v[46:49] offset:34816
	s_waitcnt lgkmcnt(0)
	s_barrier
	v_mad_u32_u24 v239, v90, s59, v92
	v_add_u32_e32 v239, s47, v239
	global_load_dwordx2 v[240:241], v239, s[40:41]
	global_load_dwordx2 v[242:243], v239, s[40:41] offset:32
	global_load_dwordx2 v[244:245], v239, s[40:41] offset:64
	global_load_dwordx2 v[246:247], v239, s[40:41] offset:96
	global_load_dwordx2 v[248:249], v239, s[40:41] offset:128
	global_load_dwordx2 v[250:251], v239, s[40:41] offset:160
	global_load_dwordx2 v[252:253], v239, s[40:41] offset:192
	global_load_dwordx2 v[254:255], v239, s[40:41] offset:224
	ds_read_b128 v[34:37], v143
	ds_read_b128 v[38:41], v143 offset:64
	ds_read_b128 v[42:45], v143 offset:4352
	ds_read_b128 v[46:49], v143 offset:4416
	s_waitcnt vmcnt(15) lgkmcnt(3)
	v_mfma_f32_16x16x32_bf16 v[34:37], v[34:37], v[6:9], 0
	ds_read_b128 v[50:53], v143 offset:8704
	ds_read_b128 v[58:61], v143 offset:8768
	s_waitcnt lgkmcnt(3)
	v_mfma_f32_16x16x32_bf16 v[42:45], v[42:45], v[6:9], 0
	s_waitcnt vmcnt(14)
	v_mfma_f32_16x16x32_bf16 v[34:37], v[38:41], v[2:5], v[34:37]
	s_waitcnt lgkmcnt(2)
	v_mfma_f32_16x16x32_bf16 v[38:41], v[46:49], v[2:5], v[42:45]
	s_nop 3
	ds_read_b128 v[42:45], v143 offset:128
	ds_read_b128 v[46:49], v143 offset:192
	s_waitcnt vmcnt(13) lgkmcnt(1)
	v_mfma_f32_16x16x32_bf16 v[34:37], v[42:45], v[10:13], v[34:37]
	ds_read_b128 v[42:45], v143 offset:4480
	ds_read_b128 v[62:65], v143 offset:4544
	v_mfma_f32_16x16x32_bf16 v[50:53], v[50:53], v[6:9], 0
	s_waitcnt lgkmcnt(1)
	v_mfma_f32_16x16x32_bf16 v[38:41], v[42:45], v[10:13], v[38:41]
	ds_read_b128 v[42:45], v143 offset:8832
	s_waitcnt vmcnt(12)
	v_mfma_f32_16x16x32_bf16 v[34:37], v[46:49], v[14:17], v[34:37]
	ds_read_b128 v[46:49], v143 offset:8896
	v_mfma_f32_16x16x32_bf16 v[50:53], v[58:61], v[2:5], v[50:53]
	v_and_b32_e32 v58, 64, v209
	s_waitcnt lgkmcnt(2)
	v_mfma_f32_16x16x32_bf16 v[38:41], v[62:65], v[14:17], v[38:41]
	v_add_u32_e32 v62, 64, v58
	ds_read_b128 v[58:61], v143 offset:13056
	v_cmp_lt_i32_e32 vcc, v0, v62
	s_waitcnt lgkmcnt(2)
	v_mfma_f32_16x16x32_bf16 v[42:45], v[42:45], v[10:13], v[50:53]
	v_cndmask_b32_e32 v0, v209, v0, vcc
	v_lshlrev_b32_e32 v91, 2, v0
	s_nop 0
	ds_read_b128 v[50:53], v143 offset:13120
	s_waitcnt lgkmcnt(2)
	v_mfma_f32_16x16x32_bf16 v[42:45], v[46:49], v[14:17], v[42:45]
	ds_read_b128 v[46:49], v143 offset:13184
	v_xor_b32_e32 v0, 32, v209
	v_cmp_lt_i32_e32 vcc, v0, v62
	s_waitcnt lgkmcnt(2)
	v_mfma_f32_16x16x32_bf16 v[58:61], v[58:61], v[6:9], 0
	ds_read_b128 v[62:65], v143 offset:13248
	v_cndmask_b32_e32 v0, v209, v0, vcc
	v_lshlrev_b32_e32 v125, 2, v0
	s_waitcnt lgkmcnt(2)
	v_mfma_f32_16x16x32_bf16 v[50:53], v[50:53], v[2:5], v[58:61]
	v_mul_u32_u24_e32 v0, 0x90, v66
	v_add3_u32 v93, 0, v92, v0
	s_waitcnt lgkmcnt(1)
	v_mfma_f32_16x16x32_bf16 v[46:49], v[46:49], v[10:13], v[50:53]
	v_mul_f32_e64 v58, v40, s34
	v_mul_f32_e64 v59, v41, s34
	v_pk_mul_f32 v[60:61], v[38:39], s[34:35] op_sel_hi:[1,0]
	v_max_f32_e32 v39, v58, v59
	s_waitcnt lgkmcnt(0)
	v_mfma_f32_16x16x32_bf16 v[46:49], v[62:65], v[14:17], v[46:49]
	v_mul_f32_e64 v62, v36, s34
	v_mul_f32_e64 v63, v37, s34
	v_pk_mul_f32 v[64:65], v[34:35], s[34:35] op_sel_hi:[1,0]
	v_pk_mul_f32 v[34:35], v[44:45], s[34:35] op_sel_hi:[1,0]
	v_max_f32_e32 v0, v64, v65
	v_max_f32_e32 v38, v62, v63
	s_nop 1
	v_pk_mul_f32 v[66:67], v[48:49], s[34:35] op_sel_hi:[1,0]
	v_max3_f32 v39, v60, v61, v39
	v_pk_mul_f32 v[36:37], v[42:43], s[34:35] op_sel_hi:[1,0]
	v_pk_mul_f32 v[68:69], v[46:47], s[34:35] op_sel_hi:[1,0]
	v_max3_f32 v0, v0, v38, v39
	v_max_f32_e32 v38, v34, v35
	v_max_f32_e32 v39, v66, v67
	v_max3_f32 v38, v36, v37, v38
	v_max3_f32 v39, v68, v69, v39
	v_max3_f32 v0, v0, v38, v39
	v_mov_b32_e32 v40, v0
	s_nop 1
	v_permlane16_swap_b32_e32 v40, v0
	v_add_co_u32_e32 v50, vcc, s6, v54
	s_waitcnt lgkmcnt(0)
	v_max_f32_e32 v40, v40, v40
	v_max_f32_e32 v0, v0, v40
	v_mov_b32_e32 v74, v0
	s_nop 1
	v_permlane32_swap_b32_e32 v74, v0
	v_addc_co_u32_e32 v51, vcc, 0, v55, vcc
	v_add_co_u32_e32 v38, vcc, s6, v56
	s_waitcnt lgkmcnt(0)
	v_max3_f32 v95, v0, v74, s14
	v_sub_f32_e32 v0, v36, v95
	v_exp_f32_e32 v94, v0
	v_sub_f32_e32 v0, v37, v95
	v_exp_f32_e32 v96, v0
	v_sub_f32_e32 v0, v34, v95
	v_exp_f32_e32 v98, v0
	v_sub_f32_e32 v0, v35, v95
	v_exp_f32_e32 v100, v0
	v_sub_f32_e32 v0, v68, v95
	v_exp_f32_e32 v102, v0
	v_sub_f32_e32 v0, v69, v95
	v_exp_f32_e32 v104, v0
	v_sub_f32_e32 v0, v66, v95
	v_exp_f32_e32 v106, v0
	v_sub_f32_e32 v0, v67, v95
	v_exp_f32_e32 v108, v0
	v_addc_co_u32_e32 v39, vcc, 0, v57, vcc
	v_cvt_pk_bf16_f32 v34, v94, v96
	v_cvt_pk_bf16_f32 v35, v98, v100
	v_cvt_pk_bf16_f32 v36, v102, v104
	v_cvt_pk_bf16_f32 v37, v106, v108
	v_mov_b32_e32 v0, v1
	global_load_dwordx4 v[42:45], v[50:51], off
	s_nop 0
	global_load_dwordx4 v[38:41], v[38:39], off
	s_nop 0
	global_load_dwordx4 v[50:53], v[70:71], off offset:256
	global_load_dwordx4 v[46:49], v[72:73], off offset:256
	s_mov_b32 s6, 0xc0000
	v_add_u32_e32 v0, v93, v0
	v_add_u32_e32 v66, 0x8800, v0
	v_add_u32_e32 v74, 0x9000, v0
	v_add_u32_e32 v97, 0x9800, v0
	ds_read2_b64 v[82:85], v66 offset1:4
	ds_read2_b64 v[86:89], v66 offset0:8 offset1:12
	ds_read2_b64 v[66:69], v74 offset0:32 offset1:36
	ds_read2_b64 v[74:77], v74 offset0:40 offset1:44
	ds_read2_b64 v[78:81], v97 offset0:64 offset1:68
	ds_read2_b64 v[126:129], v97 offset0:72 offset1:76
	v_add_u32_e32 v97, 0xa000, v0
	ds_read2_b64 v[130:133], v97 offset0:96 offset1:100
	ds_read2_b64 v[134:137], v97 offset0:104 offset1:108
	v_add_u32_e32 v97, 0xa800, v0
	ds_read2_b64 v[138:141], v97 offset0:128 offset1:132
	ds_read2_b64 v[152:155], v97 offset0:136 offset1:140
	v_add_u32_e32 v97, 0xb000, v0
	ds_read2_b64 v[158:161], v97 offset0:160 offset1:164
	ds_read2_b64 v[162:165], v97 offset0:168 offset1:172
	v_add_u32_e32 v97, 0xb800, v0
	v_add_u32_e32 v0, 0xc000, v0
	ds_read2_b64 v[166:169], v97 offset0:192 offset1:196
	ds_read2_b64 v[170:173], v97 offset0:200 offset1:204
	ds_read2_b64 v[174:177], v0 offset0:224 offset1:228
	ds_read2_b64 v[178:181], v0 offset0:232 offset1:236
	s_waitcnt vmcnt(15)
	ds_write_b128 v145, v[18:21] offset:17408
	s_waitcnt vmcnt(14)
	ds_write_b128 v147, v[22:25] offset:53248
	s_waitcnt vmcnt(13)
	ds_write_b128 v149, v[26:29] offset:17408
	s_waitcnt vmcnt(12)
	ds_write_b128 v151, v[30:33] offset:53248
	s_waitcnt lgkmcnt(0)
	s_barrier
	ds_read_b128 v[18:21], v143 offset:17408
	ds_read_b128 v[22:25], v143 offset:17472
	ds_read_b128 v[26:29], v143 offset:17536
	s_waitcnt lgkmcnt(2)
	v_mfma_f32_16x16x32_bf16 v[18:21], v[18:21], v[6:9], 0
	ds_read_b128 v[30:33], v143 offset:21824
	v_sub_f32_e32 v97, 0xf149f2ca, v95
	v_sub_f32_e32 v0, v64, v95
	s_waitcnt lgkmcnt(2)
	v_mfma_f32_16x16x32_bf16 v[18:21], v[22:25], v[2:5], v[18:21]
	ds_read_b128 v[22:25], v143 offset:17600
	v_exp_f32_e32 v0, v0
	s_waitcnt lgkmcnt(2)
	v_mfma_f32_16x16x32_bf16 v[18:21], v[26:29], v[10:13], v[18:21]
	ds_read_b128 v[26:29], v143 offset:21760
	s_waitcnt lgkmcnt(1)
	v_mfma_f32_16x16x32_bf16 v[182:185], v[22:25], v[14:17], v[18:21]
	s_nop 4
	ds_read_b128 v[18:21], v143 offset:21888
	s_waitcnt lgkmcnt(1)
	v_mfma_f32_16x16x32_bf16 v[22:25], v[26:29], v[6:9], 0
	v_sub_f32_e32 v26, v65, v95
	v_exp_f32_e32 v156, v26
	ds_read_b128 v[26:29], v143 offset:21952
	v_mfma_f32_16x16x32_bf16 v[22:25], v[30:33], v[2:5], v[22:25]
	v_sub_f32_e32 v30, v62, v95
	v_exp_f32_e32 v110, v30
	ds_read_b128 v[30:33], v143 offset:26112
	s_waitcnt lgkmcnt(2)
	v_mfma_f32_16x16x32_bf16 v[18:21], v[18:21], v[10:13], v[22:25]
	v_cvt_pk_bf16_f32 v216, v0, v156
	s_nop 1
	v_sub_f32_e32 v22, v63, v95
	v_exp_f32_e32 v112, v22
	ds_read_b128 v[22:25], v143 offset:26176
	s_waitcnt lgkmcnt(2)
	v_mfma_f32_16x16x32_bf16 v[190:193], v[26:29], v[14:17], v[18:21]
	v_cvt_pk_bf16_f32 v217, v110, v112
	s_nop 1
	v_sub_f32_e32 v18, v60, v95
	v_exp_f32_e32 v114, v18
	ds_read_b128 v[18:21], v143 offset:26240
	s_waitcnt lgkmcnt(2)
	v_mfma_f32_16x16x32_bf16 v[26:29], v[30:33], v[6:9], 0
	v_sub_f32_e32 v30, v61, v95
	v_exp_f32_e32 v116, v30
	ds_read_b128 v[30:33], v143 offset:26304
	s_waitcnt lgkmcnt(2)
	v_mfma_f32_16x16x32_bf16 v[22:25], v[22:25], v[2:5], v[26:29]
	v_cvt_pk_bf16_f32 v218, v114, v116
	s_nop 1
	v_sub_f32_e32 v26, v58, v95
	v_exp_f32_e32 v118, v26
	ds_read_b128 v[26:29], v143 offset:30464
	s_waitcnt lgkmcnt(2)
	v_mfma_f32_16x16x32_bf16 v[18:21], v[18:21], v[10:13], v[22:25]
	v_sub_f32_e32 v58, v59, v95
	v_exp_f32_e32 v59, v97
	v_exp_f32_e32 v122, v58
	ds_read_b128 v[22:25], v143 offset:30528
	s_waitcnt lgkmcnt(2)
	v_mfma_f32_16x16x32_bf16 v[194:197], v[30:33], v[14:17], v[18:21]
	ds_read_b128 v[30:33], v143 offset:30656
	v_cmp_neq_f32_e32 vcc, 1.0, v59
	s_cmp_lg_u64 vcc, 0
	ds_read_b128 v[18:21], v143 offset:30592
	s_waitcnt lgkmcnt(3)
	v_mfma_f32_16x16x32_bf16 v[26:29], v[26:29], v[6:9], 0
	v_mul_f32_e32 v120, 0, v59
	s_cselect_b64 vcc, -1, 0
	v_cndmask_b32_e32 v198, 0, v120, vcc
	s_waitcnt lgkmcnt(2)
	v_mfma_f32_16x16x32_bf16 v[22:25], v[22:25], v[2:5], v[26:29]
	v_mov_b32_e32 v199, v198
	v_mov_b32_e32 v200, v198
	v_mov_b32_e32 v201, v198
	s_waitcnt lgkmcnt(0)
	v_mfma_f32_16x16x32_bf16 v[18:21], v[18:21], v[10:13], v[22:25]
	v_cvt_pk_bf16_f32 v219, v118, v122
	v_mfma_f32_16x16x32_bf16 v[220:223], v[30:33], v[14:17], v[18:21]
	s_nop 0
	v_mfma_f32_16x16x32_bf16 v[18:21], v[66:69], v[216:219], v[198:201]
	v_mfma_f32_16x16x32_bf16 v[58:61], v[74:77], v[34:37], v[18:21]
	v_mfma_f32_16x16x32_bf16 v[18:21], v[78:81], v[216:219], v[198:201]
	v_mfma_f32_16x16x32_bf16 v[62:65], v[126:129], v[34:37], v[18:21]
	v_mul_f32_e64 v126, v192, s34
	v_mul_f32_e64 v127, v193, s34
	s_nop 0
	v_pk_mul_f32 v[128:129], v[222:223], s[34:35] op_sel_hi:[1,0]
	s_nop 2
	v_add_co_u32_e32 v18, vcc, s6, v54
	v_mfma_f32_16x16x32_bf16 v[26:29], v[130:133], v[216:219], v[198:201]
	s_nop 0
	v_addc_co_u32_e32 v19, vcc, 0, v55, vcc
	v_add_co_u32_e32 v20, vcc, s6, v56
	v_mfma_f32_16x16x32_bf16 v[66:69], v[134:137], v[34:37], v[26:29]
	s_nop 0
	v_addc_co_u32_e32 v21, vcc, 0, v57, vcc
	global_load_dwordx4 v[22:25], v[18:19], off
	s_nop 0
	global_load_dwordx4 v[18:21], v[20:21], off
	s_nop 0
	global_load_dwordx4 v[30:33], v[70:71], off offset:384
	global_load_dwordx4 v[26:29], v[72:73], off offset:384
	v_mfma_f32_16x16x32_bf16 v[54:57], v[138:141], v[216:219], v[198:201]
	v_mul_f32_e64 v136, v190, s34
	v_mul_f32_e64 v137, v191, s34
	v_pk_mul_f32 v[138:139], v[184:185], s[34:35] op_sel_hi:[1,0]
	v_pk_mul_f32 v[140:141], v[182:183], s[34:35] op_sel_hi:[1,0]
	v_mfma_f32_16x16x32_bf16 v[70:73], v[152:155], v[34:37], v[54:57]
	v_mul_f32_e64 v130, v196, s34
	v_mul_f32_e64 v131, v197, s34
	v_max_f32_e32 v78, v140, v141
	v_max_f32_e32 v79, v138, v139
	v_mfma_f32_16x16x32_bf16 v[54:57], v[158:161], v[216:219], v[198:201]
	v_mul_f32_e64 v134, v194, s34
	v_mul_f32_e64 v135, v195, s34
	v_pk_mul_f32 v[132:133], v[220:221], s[34:35] op_sel_hi:[1,0]
	v_mfma_f32_16x16x32_bf16 v[74:77], v[162:165], v[34:37], v[54:57]
	v_mfma_f32_16x16x32_bf16 v[82:85], v[82:85], v[216:219], v[198:201]
	s_nop 2
	v_max_f32_e32 v54, v126, v127
	v_max3_f32 v80, v136, v137, v54
	v_max3_f32 v97, v78, v79, v80
	v_mfma_f32_16x16x32_bf16 v[54:57], v[166:169], v[216:219], v[198:201]
	v_max_f32_e32 v78, v130, v131
	v_max3_f32 v99, v134, v135, v78
	v_mfma_f32_16x16x32_bf16 v[78:81], v[170:173], v[34:37], v[54:57]
	s_nop 4
	v_max_f32_e32 v54, v128, v129
	v_max3_f32 v54, v132, v133, v54
	v_max3_f32 v97, v97, v99, v54
	v_mov_b32_e32 v99, v97
	s_nop 1
	v_permlane16_swap_b32_e32 v99, v97
	v_mfma_f32_16x16x32_bf16 v[54:57], v[174:177], v[216:219], v[198:201]
	s_waitcnt lgkmcnt(0)
	v_max_f32_e32 v99, v99, v99
	v_max_f32_e32 v97, v97, v99
	v_mov_b32_e32 v99, v97
	s_nop 1
	v_permlane32_swap_b32_e32 v99, v97
	v_mfma_f32_16x16x32_bf16 v[54:57], v[178:181], v[34:37], v[54:57]
	s_waitcnt lgkmcnt(0)
	v_max3_f32 v142, v95, v97, v99
	v_sub_f32_e32 v95, v95, v142
	v_exp_f32_e32 v124, v95
	v_mfma_f32_16x16x32_bf16 v[34:37], v[86:89], v[34:37], v[82:85]
	v_cmp_neq_f32_e32 vcc, 1.0, v124
	s_cbranch_vccz .LBB0_405
	s_nop 5
	v_pk_mul_f32 v[36:37], v[36:37], v[124:125] op_sel_hi:[1,0]
	v_pk_mul_f32 v[34:35], v[34:35], v[124:125] op_sel_hi:[1,0]
	v_pk_mul_f32 v[60:61], v[60:61], v[124:125] op_sel_hi:[1,0]
	v_pk_mul_f32 v[58:59], v[58:59], v[124:125] op_sel_hi:[1,0]
	v_pk_mul_f32 v[64:65], v[64:65], v[124:125] op_sel_hi:[1,0]
	v_pk_mul_f32 v[62:63], v[62:63], v[124:125] op_sel_hi:[1,0]
	v_pk_mul_f32 v[68:69], v[68:69], v[124:125] op_sel_hi:[1,0]
	v_pk_mul_f32 v[66:67], v[66:67], v[124:125] op_sel_hi:[1,0]
	v_pk_mul_f32 v[72:73], v[72:73], v[124:125] op_sel_hi:[1,0]
	v_pk_mul_f32 v[70:71], v[70:71], v[124:125] op_sel_hi:[1,0]
	v_pk_mul_f32 v[76:77], v[76:77], v[124:125] op_sel_hi:[1,0]
	v_pk_mul_f32 v[74:75], v[74:75], v[124:125] op_sel_hi:[1,0]
	v_pk_mul_f32 v[80:81], v[80:81], v[124:125] op_sel_hi:[1,0]
	v_pk_mul_f32 v[78:79], v[78:79], v[124:125] op_sel_hi:[1,0]
	v_pk_mul_f32 v[56:57], v[56:57], v[124:125] op_sel_hi:[1,0]
	v_pk_mul_f32 v[54:55], v[54:55], v[124:125] op_sel_hi:[1,0]
